# epilogue row-sum reductions (FFN down, kv up-proj, W_out, w_in): ds_bpermute pairs replaced by v_permlane32_swap/v_permlane16_swap
# baseline (speedup 1.0000x reference)
.LBB0_198:
	s_or_b64 exec, exec, s[44:45]
	v_or_b32_e32 v116, 16, v142
	v_ashrrev_i32_e32 v117, 31, v116
	s_waitcnt lgkmcnt(0)
	v_lshlrev_b64 v[114:115], 11, v[116:117]
	v_lshl_add_u64 v[114:115], s[38:39], 0, v[114:115]
	v_lshlrev_b32_e32 v119, 3, v147
	v_lshl_add_u64 v[114:115], s[40:41], 1, v[114:115]
	v_lshl_add_u64 v[120:121], v[114:115], 0, v[80:81]
	v_lshlrev_b32_e32 v114, 1, v119
	v_mov_b32_e32 v115, v81
	v_lshl_add_u64 v[128:129], v[120:121], 0, v[114:115]
	s_waitcnt vmcnt(14)
	v_lshlrev_b32_e32 v148, 16, v176
	v_and_b32_e32 v149, 0xffff0000, v176
	v_pk_fma_f32 v[110:111], v[110:111], 0.5, v[148:149] op_sel_hi:[1,0,1]
	v_lshlrev_b32_e32 v120, 16, v177
	v_and_b32_e32 v121, 0xffff0000, v177
	v_lshlrev_b32_e32 v150, 16, v178
	v_and_b32_e32 v151, 0xffff0000, v178
	v_lshlrev_b32_e32 v122, 16, v179
	v_and_b32_e32 v123, 0xffff0000, v179
	v_mul_f32_e32 v119, v111, v111
	v_pk_fma_f32 v[112:113], v[112:113], 0.5, v[120:121] op_sel_hi:[1,0,1]
	v_pk_fma_f32 v[120:121], v[108:109], 0.5, v[122:123] op_sel_hi:[1,0,1]
	v_pk_fma_f32 v[122:123], v[106:107], 0.5, v[150:151] op_sel_hi:[1,0,1]
	v_cvt_pk_bf16_f32 v106, v110, v111
	v_cvt_pk_bf16_f32 v107, v112, v113
	v_fmac_f32_e32 v119, v110, v110
	v_cvt_pk_bf16_f32 v108, v122, v123
	v_cvt_pk_bf16_f32 v109, v120, v121
	global_store_dwordx4 v[128:129], v[106:109], off
	v_fmac_f32_e32 v119, v112, v112
	v_lshlrev_b32_e32 v110, 16, v182
	v_lshlrev_b32_e32 v106, 16, v180
	v_and_b32_e32 v107, 0xffff0000, v180
	v_lshlrev_b32_e32 v108, 16, v181
	v_and_b32_e32 v109, 0xffff0000, v181
	v_and_b32_e32 v111, 0xffff0000, v182
	v_fmac_f32_e32 v119, v113, v113
	v_lshlrev_b32_e32 v112, 16, v183
	v_and_b32_e32 v113, 0xffff0000, v183
	v_pk_fma_f32 v[104:105], v[104:105], 0.5, v[108:109] op_sel_hi:[1,0,1]
	v_pk_fma_f32 v[102:103], v[102:103], 0.5, v[106:107] op_sel_hi:[1,0,1]
	v_pk_fma_f32 v[108:109], v[98:99], 0.5, v[110:111] op_sel_hi:[1,0,1]
	v_cvt_pk_bf16_f32 v98, v102, v103
	v_pk_fma_f32 v[106:107], v[100:101], 0.5, v[112:113] op_sel_hi:[1,0,1]
	v_cvt_pk_bf16_f32 v99, v104, v105
	v_cvt_pk_bf16_f32 v100, v108, v109
	v_fmac_f32_e32 v119, v122, v122
	v_cvt_pk_bf16_f32 v101, v106, v107
	global_store_dwordx4 v[128:129], v[98:101], off offset:256
	v_fmac_f32_e32 v119, v123, v123
	v_fmac_f32_e32 v119, v120, v120
	v_mul_f32_e32 v98, v103, v103
	v_fmac_f32_e32 v98, v102, v102
	v_fmac_f32_e32 v98, v104, v104
	v_fmac_f32_e32 v98, v105, v105
	v_fmac_f32_e32 v98, v108, v108
	v_fmac_f32_e32 v98, v109, v109
	v_fmac_f32_e32 v98, v106, v106
	v_fmac_f32_e32 v119, v121, v121
	v_fmac_f32_e32 v98, v107, v107
	v_add_f32_e32 v98, v119, v98
	v_mov_b32_e32 v99, v98
	s_nop 1
	v_permlane32_swap_b32 v99, v98
	s_nop 1
	s_waitcnt lgkmcnt(0)
	v_add_f32_e32 v98, v98, v99
	v_mov_b32_e32 v99, v98
	s_nop 1
	v_permlane16_swap_b32 v99, v98
	s_nop 1
	s_and_saveexec_b64 s[44:45], vcc
	s_cbranch_execz .LBB0_200
	v_readlane_b32 s54, v253, 14
	v_readlane_b32 s55, v253, 15
	s_waitcnt lgkmcnt(0)
	v_add_f32_e32 v98, v98, v99
	v_lshl_add_u64 v[100:101], v[116:117], 2, s[54:55]
	global_atomic_add_f32 v[100:101], v98, off
.LBB0_200:
	s_or_b64 exec, exec, s[44:45]
	v_or_b32_e32 v98, 32, v142
	s_waitcnt lgkmcnt(0)
	v_ashrrev_i32_e32 v99, 31, v98
	v_lshlrev_b64 v[100:101], 11, v[98:99]
	v_lshl_add_u64 v[100:101], s[38:39], 0, v[100:101]
	v_lshl_add_u64 v[100:101], s[40:41], 1, v[100:101]
	v_lshl_add_u64 v[100:101], v[100:101], 0, v[80:81]
	v_lshl_add_u64 v[108:109], v[100:101], 0, v[114:115]
	s_waitcnt vmcnt(14)
	v_lshlrev_b32_e32 v110, 16, v184
	v_and_b32_e32 v111, 0xffff0000, v184
	v_pk_fma_f32 v[94:95], v[94:95], 0.5, v[110:111] op_sel_hi:[1,0,1]
	v_lshlrev_b32_e32 v100, 16, v185
	v_and_b32_e32 v101, 0xffff0000, v185
	v_lshlrev_b32_e32 v112, 16, v186
	v_and_b32_e32 v113, 0xffff0000, v186
	v_lshlrev_b32_e32 v102, 16, v187
	v_and_b32_e32 v103, 0xffff0000, v187
	v_mul_f32_e32 v110, v95, v95
	v_pk_fma_f32 v[96:97], v[96:97], 0.5, v[100:101] op_sel_hi:[1,0,1]
	v_pk_fma_f32 v[100:101], v[92:93], 0.5, v[102:103] op_sel_hi:[1,0,1]
	v_pk_fma_f32 v[102:103], v[90:91], 0.5, v[112:113] op_sel_hi:[1,0,1]
	v_cvt_pk_bf16_f32 v90, v94, v95
	v_cvt_pk_bf16_f32 v91, v96, v97
	v_fmac_f32_e32 v110, v94, v94
	v_cvt_pk_bf16_f32 v92, v102, v103
	v_cvt_pk_bf16_f32 v93, v100, v101
	global_store_dwordx4 v[108:109], v[90:93], off
	v_fmac_f32_e32 v110, v96, v96
	v_lshlrev_b32_e32 v94, 16, v190
	v_lshlrev_b32_e32 v90, 16, v188
	v_and_b32_e32 v91, 0xffff0000, v188
	v_lshlrev_b32_e32 v92, 16, v189
	v_and_b32_e32 v93, 0xffff0000, v189
	v_and_b32_e32 v95, 0xffff0000, v190
	v_fmac_f32_e32 v110, v97, v97
	v_lshlrev_b32_e32 v96, 16, v191
	v_and_b32_e32 v97, 0xffff0000, v191
	v_pk_fma_f32 v[88:89], v[88:89], 0.5, v[92:93] op_sel_hi:[1,0,1]
	v_pk_fma_f32 v[86:87], v[86:87], 0.5, v[90:91] op_sel_hi:[1,0,1]
	v_pk_fma_f32 v[92:93], v[82:83], 0.5, v[94:95] op_sel_hi:[1,0,1]
	v_cvt_pk_bf16_f32 v82, v86, v87
	v_pk_fma_f32 v[90:91], v[84:85], 0.5, v[96:97] op_sel_hi:[1,0,1]
	v_cvt_pk_bf16_f32 v83, v88, v89
	v_cvt_pk_bf16_f32 v84, v92, v93
	v_fmac_f32_e32 v110, v102, v102
	v_cvt_pk_bf16_f32 v85, v90, v91
	global_store_dwordx4 v[108:109], v[82:85], off offset:256
	v_fmac_f32_e32 v110, v103, v103
	v_fmac_f32_e32 v110, v100, v100
	v_mul_f32_e32 v82, v87, v87
	v_fmac_f32_e32 v82, v86, v86
	v_fmac_f32_e32 v82, v88, v88
	v_fmac_f32_e32 v82, v89, v89
	v_fmac_f32_e32 v82, v92, v92
	v_fmac_f32_e32 v82, v93, v93
	v_fmac_f32_e32 v82, v90, v90
	v_fmac_f32_e32 v110, v101, v101
	v_fmac_f32_e32 v82, v91, v91
	v_add_f32_e32 v82, v110, v82
	v_mov_b32_e32 v83, v82
	s_nop 1
	v_permlane32_swap_b32 v83, v82
	s_nop 1
	s_waitcnt lgkmcnt(0)
	v_add_f32_e32 v82, v82, v83
	v_mov_b32_e32 v83, v82
	s_nop 1
	v_permlane16_swap_b32 v83, v82
	s_nop 1
	s_and_saveexec_b64 s[44:45], vcc
	s_cbranch_execz .LBB0_202
	v_readlane_b32 s54, v253, 14
	v_readlane_b32 s55, v253, 15
	s_waitcnt lgkmcnt(0)
	v_add_f32_e32 v82, v82, v83
	v_lshl_add_u64 v[84:85], v[98:99], 2, s[54:55]
	global_atomic_add_f32 v[84:85], v82, off
.LBB0_202:
	s_or_b64 exec, exec, s[44:45]
	v_or_b32_e32 v82, 48, v142
	s_waitcnt lgkmcnt(0)
	v_ashrrev_i32_e32 v83, 31, v82
	v_lshlrev_b64 v[84:85], 11, v[82:83]
	v_lshl_add_u64 v[84:85], s[38:39], 0, v[84:85]
	v_lshl_add_u64 v[84:85], s[40:41], 1, v[84:85]
	v_lshl_add_u64 v[84:85], v[84:85], 0, v[80:81]
	v_mov_b32_e32 v115, v81
	v_lshl_add_u64 v[92:93], v[84:85], 0, v[114:115]
	s_waitcnt vmcnt(14)
	v_lshlrev_b32_e32 v94, 16, v204
	v_and_b32_e32 v95, 0xffff0000, v204
	v_pk_fma_f32 v[76:77], v[76:77], 0.5, v[94:95] op_sel_hi:[1,0,1]
	v_lshlrev_b32_e32 v84, 16, v205
	v_and_b32_e32 v85, 0xffff0000, v205
	v_lshlrev_b32_e32 v96, 16, v206
	v_and_b32_e32 v97, 0xffff0000, v206
	v_lshlrev_b32_e32 v86, 16, v207
	v_and_b32_e32 v87, 0xffff0000, v207
	v_mul_f32_e32 v94, v77, v77
	v_pk_fma_f32 v[78:79], v[78:79], 0.5, v[84:85] op_sel_hi:[1,0,1]
	v_pk_fma_f32 v[84:85], v[74:75], 0.5, v[86:87] op_sel_hi:[1,0,1]
	v_pk_fma_f32 v[86:87], v[72:73], 0.5, v[96:97] op_sel_hi:[1,0,1]
	v_cvt_pk_bf16_f32 v72, v76, v77
	v_cvt_pk_bf16_f32 v73, v78, v79
	v_fmac_f32_e32 v94, v76, v76
	v_cvt_pk_bf16_f32 v74, v86, v87
	v_cvt_pk_bf16_f32 v75, v84, v85
	global_store_dwordx4 v[92:93], v[72:75], off
	v_fmac_f32_e32 v94, v78, v78
	v_lshlrev_b32_e32 v76, 16, v210
	v_lshlrev_b32_e32 v72, 16, v208
	v_and_b32_e32 v73, 0xffff0000, v208
	v_lshlrev_b32_e32 v74, 16, v209
	v_and_b32_e32 v75, 0xffff0000, v209
	v_and_b32_e32 v77, 0xffff0000, v210
	v_fmac_f32_e32 v94, v79, v79
	v_lshlrev_b32_e32 v78, 16, v211
	v_and_b32_e32 v79, 0xffff0000, v211
	v_pk_fma_f32 v[70:71], v[70:71], 0.5, v[74:75] op_sel_hi:[1,0,1]
	v_pk_fma_f32 v[68:69], v[68:69], 0.5, v[72:73] op_sel_hi:[1,0,1]
	v_pk_fma_f32 v[74:75], v[64:65], 0.5, v[76:77] op_sel_hi:[1,0,1]
	v_cvt_pk_bf16_f32 v64, v68, v69
	v_pk_fma_f32 v[72:73], v[66:67], 0.5, v[78:79] op_sel_hi:[1,0,1]
	v_cvt_pk_bf16_f32 v65, v70, v71
	v_cvt_pk_bf16_f32 v66, v74, v75
	v_fmac_f32_e32 v94, v86, v86
	v_cvt_pk_bf16_f32 v67, v72, v73
	global_store_dwordx4 v[92:93], v[64:67], off offset:256
	v_fmac_f32_e32 v94, v87, v87
	v_fmac_f32_e32 v94, v84, v84
	v_mul_f32_e32 v64, v69, v69
	v_fmac_f32_e32 v64, v68, v68
	v_fmac_f32_e32 v64, v70, v70
	v_fmac_f32_e32 v64, v71, v71
	v_fmac_f32_e32 v64, v74, v74
	v_fmac_f32_e32 v64, v75, v75
	v_fmac_f32_e32 v64, v72, v72
	v_fmac_f32_e32 v94, v85, v85
	v_fmac_f32_e32 v64, v73, v73
	v_add_f32_e32 v64, v94, v64
	v_mov_b32_e32 v65, v64
	s_nop 1
	v_permlane32_swap_b32 v65, v64
	s_nop 1
	s_waitcnt lgkmcnt(0)
	v_add_f32_e32 v64, v64, v65
	v_mov_b32_e32 v65, v64
	s_nop 1
	v_permlane16_swap_b32 v65, v64
	s_nop 1
	s_and_saveexec_b64 s[44:45], vcc
	s_cbranch_execz .LBB0_204
	v_readlane_b32 s54, v253, 14
	v_readlane_b32 s55, v253, 15
	s_waitcnt lgkmcnt(0)
	v_add_f32_e32 v64, v64, v65
	v_lshl_add_u64 v[66:67], v[82:83], 2, s[54:55]
	global_atomic_add_f32 v[66:67], v64, off
.LBB0_204:
	s_or_b64 exec, exec, s[44:45]
	v_add_u32_e32 v64, 0x80, v142
	s_waitcnt lgkmcnt(0)
	v_ashrrev_i32_e32 v65, 31, v64
	v_lshlrev_b64 v[66:67], 11, v[64:65]
	v_lshl_add_u64 v[66:67], s[38:39], 0, v[66:67]
	v_lshl_add_u64 v[66:67], s[40:41], 1, v[66:67]
	v_lshl_add_u64 v[66:67], v[66:67], 0, v[80:81]
	v_lshl_add_u64 v[74:75], v[66:67], 0, v[114:115]
	s_waitcnt vmcnt(14)
	v_lshlrev_b32_e32 v76, 16, v212
	v_and_b32_e32 v77, 0xffff0000, v212
	v_pk_fma_f32 v[60:61], v[60:61], 0.5, v[76:77] op_sel_hi:[1,0,1]
	v_lshlrev_b32_e32 v66, 16, v213
	v_and_b32_e32 v67, 0xffff0000, v213
	v_lshlrev_b32_e32 v78, 16, v214
	v_and_b32_e32 v79, 0xffff0000, v214
	v_lshlrev_b32_e32 v68, 16, v215
	v_and_b32_e32 v69, 0xffff0000, v215
	v_mul_f32_e32 v76, v61, v61
	v_pk_fma_f32 v[62:63], v[62:63], 0.5, v[66:67] op_sel_hi:[1,0,1]
	v_pk_fma_f32 v[66:67], v[58:59], 0.5, v[68:69] op_sel_hi:[1,0,1]
	v_pk_fma_f32 v[68:69], v[56:57], 0.5, v[78:79] op_sel_hi:[1,0,1]
	v_cvt_pk_bf16_f32 v56, v60, v61
	v_cvt_pk_bf16_f32 v57, v62, v63
	v_fmac_f32_e32 v76, v60, v60
	v_cvt_pk_bf16_f32 v58, v68, v69
	v_cvt_pk_bf16_f32 v59, v66, v67
	global_store_dwordx4 v[74:75], v[56:59], off
	v_fmac_f32_e32 v76, v62, v62
	v_lshlrev_b32_e32 v60, 16, v218
	v_lshlrev_b32_e32 v56, 16, v216
	v_and_b32_e32 v57, 0xffff0000, v216
	v_lshlrev_b32_e32 v58, 16, v217
	v_and_b32_e32 v59, 0xffff0000, v217
	v_and_b32_e32 v61, 0xffff0000, v218
	v_fmac_f32_e32 v76, v63, v63
	v_lshlrev_b32_e32 v62, 16, v219
	v_and_b32_e32 v63, 0xffff0000, v219
	v_pk_fma_f32 v[54:55], v[54:55], 0.5, v[58:59] op_sel_hi:[1,0,1]
	v_pk_fma_f32 v[52:53], v[52:53], 0.5, v[56:57] op_sel_hi:[1,0,1]
	v_pk_fma_f32 v[58:59], v[48:49], 0.5, v[60:61] op_sel_hi:[1,0,1]
	v_cvt_pk_bf16_f32 v48, v52, v53
	v_pk_fma_f32 v[56:57], v[50:51], 0.5, v[62:63] op_sel_hi:[1,0,1]
	v_cvt_pk_bf16_f32 v49, v54, v55
	v_cvt_pk_bf16_f32 v50, v58, v59
	v_fmac_f32_e32 v76, v68, v68
	v_cvt_pk_bf16_f32 v51, v56, v57
	global_store_dwordx4 v[74:75], v[48:51], off offset:256
	v_fmac_f32_e32 v76, v69, v69
	v_fmac_f32_e32 v76, v66, v66
	v_mul_f32_e32 v48, v53, v53
	v_fmac_f32_e32 v48, v52, v52
	v_fmac_f32_e32 v48, v54, v54
	v_fmac_f32_e32 v48, v55, v55
	v_fmac_f32_e32 v48, v58, v58
	v_fmac_f32_e32 v48, v59, v59
	v_fmac_f32_e32 v48, v56, v56
	v_fmac_f32_e32 v76, v67, v67
	v_fmac_f32_e32 v48, v57, v57
	v_add_f32_e32 v48, v76, v48
	v_mov_b32_e32 v49, v48
	s_nop 1
	v_permlane32_swap_b32 v49, v48
	s_nop 1
	s_waitcnt lgkmcnt(0)
	v_add_f32_e32 v48, v48, v49
	v_mov_b32_e32 v49, v48
	s_nop 1
	v_permlane16_swap_b32 v49, v48
	s_nop 1
	s_and_saveexec_b64 s[44:45], vcc
	s_cbranch_execz .LBB0_206
	v_readlane_b32 s54, v253, 14
	v_readlane_b32 s55, v253, 15
	s_waitcnt lgkmcnt(0)
	v_add_f32_e32 v48, v48, v49
	v_lshl_add_u64 v[50:51], v[64:65], 2, s[54:55]
	global_atomic_add_f32 v[50:51], v48, off
.LBB0_206:
	s_or_b64 exec, exec, s[44:45]
	v_add_u32_e32 v48, 0x90, v142
	s_waitcnt lgkmcnt(0)
	v_ashrrev_i32_e32 v49, 31, v48
	v_lshlrev_b64 v[50:51], 11, v[48:49]
	v_lshl_add_u64 v[50:51], s[38:39], 0, v[50:51]
	v_lshl_add_u64 v[50:51], s[40:41], 1, v[50:51]
	v_lshl_add_u64 v[50:51], v[50:51], 0, v[80:81]
	v_mov_b32_e32 v115, v81
	v_lshl_add_u64 v[58:59], v[50:51], 0, v[114:115]
	s_waitcnt vmcnt(14)
	v_lshlrev_b32_e32 v60, 16, v220
	v_and_b32_e32 v61, 0xffff0000, v220
	v_pk_fma_f32 v[44:45], v[44:45], 0.5, v[60:61] op_sel_hi:[1,0,1]
	v_lshlrev_b32_e32 v50, 16, v221
	v_and_b32_e32 v51, 0xffff0000, v221
	v_lshlrev_b32_e32 v62, 16, v222
	v_and_b32_e32 v63, 0xffff0000, v222
	v_lshlrev_b32_e32 v52, 16, v223
	v_and_b32_e32 v53, 0xffff0000, v223
	v_mul_f32_e32 v60, v45, v45
	v_pk_fma_f32 v[46:47], v[46:47], 0.5, v[50:51] op_sel_hi:[1,0,1]
	v_pk_fma_f32 v[50:51], v[42:43], 0.5, v[52:53] op_sel_hi:[1,0,1]
	v_pk_fma_f32 v[52:53], v[40:41], 0.5, v[62:63] op_sel_hi:[1,0,1]
	v_cvt_pk_bf16_f32 v40, v44, v45
	v_cvt_pk_bf16_f32 v41, v46, v47
	v_fmac_f32_e32 v60, v44, v44
	v_cvt_pk_bf16_f32 v42, v52, v53
	v_cvt_pk_bf16_f32 v43, v50, v51
	global_store_dwordx4 v[58:59], v[40:43], off
	v_fmac_f32_e32 v60, v46, v46
	v_lshlrev_b32_e32 v44, 16, v226
	v_lshlrev_b32_e32 v40, 16, v224
	v_and_b32_e32 v41, 0xffff0000, v224
	v_lshlrev_b32_e32 v42, 16, v225
	v_and_b32_e32 v43, 0xffff0000, v225
	v_and_b32_e32 v45, 0xffff0000, v226
	v_fmac_f32_e32 v60, v47, v47
	v_lshlrev_b32_e32 v46, 16, v227
	v_and_b32_e32 v47, 0xffff0000, v227
	v_pk_fma_f32 v[38:39], v[38:39], 0.5, v[42:43] op_sel_hi:[1,0,1]
	v_pk_fma_f32 v[36:37], v[36:37], 0.5, v[40:41] op_sel_hi:[1,0,1]
	v_pk_fma_f32 v[42:43], v[32:33], 0.5, v[44:45] op_sel_hi:[1,0,1]
	v_cvt_pk_bf16_f32 v32, v36, v37
	v_pk_fma_f32 v[40:41], v[34:35], 0.5, v[46:47] op_sel_hi:[1,0,1]
	v_cvt_pk_bf16_f32 v33, v38, v39
	v_cvt_pk_bf16_f32 v34, v42, v43
	v_fmac_f32_e32 v60, v52, v52
	v_cvt_pk_bf16_f32 v35, v40, v41
	global_store_dwordx4 v[58:59], v[32:35], off offset:256
	v_fmac_f32_e32 v60, v53, v53
	v_fmac_f32_e32 v60, v50, v50
	v_mul_f32_e32 v32, v37, v37
	v_fmac_f32_e32 v32, v36, v36
	v_fmac_f32_e32 v32, v38, v38
	v_fmac_f32_e32 v32, v39, v39
	v_fmac_f32_e32 v32, v42, v42
	v_fmac_f32_e32 v32, v43, v43
	v_fmac_f32_e32 v32, v40, v40
	v_fmac_f32_e32 v60, v51, v51
	v_fmac_f32_e32 v32, v41, v41
	v_add_f32_e32 v32, v60, v32
	v_mov_b32_e32 v33, v32
	s_nop 1
	v_permlane32_swap_b32 v33, v32
	s_nop 1
	s_waitcnt lgkmcnt(0)
	v_add_f32_e32 v32, v32, v33
	v_mov_b32_e32 v33, v32
	s_nop 1
	v_permlane16_swap_b32 v33, v32
	s_nop 1
	s_and_saveexec_b64 s[44:45], vcc
	s_cbranch_execz .LBB0_208
	v_readlane_b32 s54, v253, 14
	v_readlane_b32 s55, v253, 15
	s_waitcnt lgkmcnt(0)
	v_add_f32_e32 v32, v32, v33
	v_lshl_add_u64 v[34:35], v[48:49], 2, s[54:55]
	global_atomic_add_f32 v[34:35], v32, off
.LBB0_208:
	s_or_b64 exec, exec, s[44:45]
	v_add_u32_e32 v32, 0xa0, v142
	s_waitcnt lgkmcnt(0)
	v_ashrrev_i32_e32 v33, 31, v32
	v_lshlrev_b64 v[34:35], 11, v[32:33]
	v_lshl_add_u64 v[34:35], s[38:39], 0, v[34:35]
	v_lshl_add_u64 v[34:35], s[40:41], 1, v[34:35]
	v_lshl_add_u64 v[34:35], v[34:35], 0, v[80:81]
	v_lshl_add_u64 v[42:43], v[34:35], 0, v[114:115]
	s_waitcnt vmcnt(14)
	v_lshlrev_b32_e32 v44, 16, v228
	v_and_b32_e32 v45, 0xffff0000, v228
	v_pk_fma_f32 v[28:29], v[28:29], 0.5, v[44:45] op_sel_hi:[1,0,1]
	v_lshlrev_b32_e32 v34, 16, v229
	v_and_b32_e32 v35, 0xffff0000, v229
	v_lshlrev_b32_e32 v46, 16, v230
	v_and_b32_e32 v47, 0xffff0000, v230
	v_lshlrev_b32_e32 v36, 16, v231
	v_and_b32_e32 v37, 0xffff0000, v231
	v_mul_f32_e32 v44, v29, v29
	v_pk_fma_f32 v[30:31], v[30:31], 0.5, v[34:35] op_sel_hi:[1,0,1]
	v_pk_fma_f32 v[34:35], v[26:27], 0.5, v[36:37] op_sel_hi:[1,0,1]
	v_pk_fma_f32 v[36:37], v[24:25], 0.5, v[46:47] op_sel_hi:[1,0,1]
	v_cvt_pk_bf16_f32 v24, v28, v29
	v_cvt_pk_bf16_f32 v25, v30, v31
	v_fmac_f32_e32 v44, v28, v28
	v_cvt_pk_bf16_f32 v26, v36, v37
	v_cvt_pk_bf16_f32 v27, v34, v35
	global_store_dwordx4 v[42:43], v[24:27], off
	v_fmac_f32_e32 v44, v30, v30
	v_lshlrev_b32_e32 v28, 16, v234
	v_lshlrev_b32_e32 v24, 16, v232
	v_and_b32_e32 v25, 0xffff0000, v232
	v_lshlrev_b32_e32 v26, 16, v233
	v_and_b32_e32 v27, 0xffff0000, v233
	v_and_b32_e32 v29, 0xffff0000, v234
	v_fmac_f32_e32 v44, v31, v31
	v_lshlrev_b32_e32 v30, 16, v235
	v_and_b32_e32 v31, 0xffff0000, v235
	v_pk_fma_f32 v[22:23], v[22:23], 0.5, v[26:27] op_sel_hi:[1,0,1]
	v_pk_fma_f32 v[20:21], v[20:21], 0.5, v[24:25] op_sel_hi:[1,0,1]
	v_pk_fma_f32 v[26:27], v[16:17], 0.5, v[28:29] op_sel_hi:[1,0,1]
	v_cvt_pk_bf16_f32 v16, v20, v21
	v_pk_fma_f32 v[24:25], v[18:19], 0.5, v[30:31] op_sel_hi:[1,0,1]
	v_cvt_pk_bf16_f32 v17, v22, v23
	v_cvt_pk_bf16_f32 v18, v26, v27
	v_fmac_f32_e32 v44, v36, v36
	v_cvt_pk_bf16_f32 v19, v24, v25
	global_store_dwordx4 v[42:43], v[16:19], off offset:256
	v_fmac_f32_e32 v44, v37, v37
	v_fmac_f32_e32 v44, v34, v34
	v_mul_f32_e32 v16, v21, v21
	v_fmac_f32_e32 v16, v20, v20
	v_fmac_f32_e32 v16, v22, v22
	v_fmac_f32_e32 v16, v23, v23
	v_fmac_f32_e32 v16, v26, v26
	v_fmac_f32_e32 v16, v27, v27
	v_fmac_f32_e32 v16, v24, v24
	v_fmac_f32_e32 v44, v35, v35
	v_fmac_f32_e32 v16, v25, v25
	v_add_f32_e32 v16, v44, v16
	v_mov_b32_e32 v17, v16
	s_nop 1
	v_permlane32_swap_b32 v17, v16
	s_nop 1
	s_waitcnt lgkmcnt(0)
	v_add_f32_e32 v16, v16, v17
	v_mov_b32_e32 v17, v16
	s_nop 1
	v_permlane16_swap_b32 v17, v16
	s_nop 1
	s_and_saveexec_b64 s[44:45], vcc
	s_cbranch_execz .LBB0_210
	v_readlane_b32 s54, v253, 14
	v_readlane_b32 s55, v253, 15
	s_waitcnt lgkmcnt(0)
	v_add_f32_e32 v16, v16, v17
	v_lshl_add_u64 v[18:19], v[32:33], 2, s[54:55]
	global_atomic_add_f32 v[18:19], v16, off

.LBB0_311:
	s_add_i32 s4, s11, -4
	s_cmp_lt_u32 s4, 5
	s_cselect_b64 s[56:57], -1, 0
	s_cmp_gt_u32 s4, 4
	s_cbranch_scc1 .LBB0_315
	v_xor_b32_e32 v80, 16, v195
	v_cmp_lt_i32_e32 vcc, v80, v197
	s_nop 1
	v_cndmask_b32_e32 v80, v195, v80, vcc
	v_lshlrev_b32_e32 v80, 2, v80
	v_mov_b32_e32 v80, v165
	s_nop 1
	v_permlane32_swap_b32 v80, v165
	s_nop 1
	v_cmp_lt_i32_e32 vcc, v196, v197
	s_waitcnt lgkmcnt(0)
	v_add_f32_e32 v80, v165, v80
	v_cndmask_b32_e32 v122, v195, v196, vcc
	v_lshlrev_b32_e32 v122, 2, v122
	v_mov_b32_e32 v122, v80
	s_nop 1
	v_permlane16_swap_b32 v122, v80
	s_nop 1
	s_and_saveexec_b64 s[52:53], s[46:47]
	s_cbranch_execz .LBB0_314
	s_cmp_lt_u32 s11, 7
	s_cselect_b32 s4, s16, 0xa0000
	v_lshl_add_u64 v[124:125], v[166:167], 0, s[4:5]
	s_waitcnt lgkmcnt(0)
	v_add_f32_e32 v80, v80, v122
	global_atomic_add_f32 v[124:125], v80, off

.LBB0_331:
	s_add_i32 s4, s11, -3
	s_cmp_lt_u32 s4, 5
	s_cselect_b64 s[60:61], -1, 0
	s_cmp_gt_u32 s4, 4
	s_cbranch_scc1 .LBB0_335
	v_xor_b32_e32 v80, 16, v195
	v_cmp_lt_i32_e32 vcc, v80, v197
	s_nop 1
	v_cndmask_b32_e32 v80, v195, v80, vcc
	v_lshlrev_b32_e32 v80, 2, v80
	v_mov_b32_e32 v80, v165
	s_nop 1
	v_permlane32_swap_b32 v80, v165
	s_nop 1
	v_cmp_lt_i32_e32 vcc, v196, v197
	s_waitcnt lgkmcnt(0)
	v_add_f32_e32 v80, v165, v80
	v_cndmask_b32_e32 v114, v195, v196, vcc
	v_lshlrev_b32_e32 v114, 2, v114
	v_mov_b32_e32 v114, v80
	s_nop 1
	v_permlane16_swap_b32 v114, v80
	s_nop 1
	s_and_saveexec_b64 s[54:55], s[46:47]
	s_cbranch_execz .LBB0_334
	s_cmp_lt_u32 s43, 7
	s_cselect_b32 s4, s16, 0xa0000
	v_lshl_add_u64 v[116:117], v[166:167], 0, s[4:5]
	s_waitcnt lgkmcnt(0)
	v_add_f32_e32 v80, v80, v114
	global_atomic_add_f32 v[116:117], v80, off

.LBB0_351:
	v_cndmask_b32_e64 v80, 0, 1, s[56:57]
	v_cmp_ne_u32_e64 s[54:55], 1, v80
	s_andn2_b64 vcc, exec, s[56:57]
	s_cbranch_vccnz .LBB0_355
	v_xor_b32_e32 v80, 16, v195
	v_cmp_lt_i32_e32 vcc, v80, v197
	s_nop 1
	v_cndmask_b32_e32 v80, v195, v80, vcc
	v_lshlrev_b32_e32 v80, 2, v80
	v_mov_b32_e32 v80, v139
	s_nop 1
	v_permlane32_swap_b32 v80, v139
	s_nop 1
	v_cmp_lt_i32_e32 vcc, v196, v197
	s_waitcnt lgkmcnt(0)
	v_add_f32_e32 v80, v139, v80
	v_cndmask_b32_e32 v106, v195, v196, vcc
	v_lshlrev_b32_e32 v106, 2, v106
	v_mov_b32_e32 v106, v80
	s_nop 1
	v_permlane16_swap_b32 v106, v80
	s_nop 1
	s_and_saveexec_b64 s[56:57], s[46:47]
	s_cbranch_execz .LBB0_354
	s_cmp_lt_u32 s11, 7
	s_cselect_b32 s4, s16, 0xa0000
	v_lshl_add_u64 v[108:109], v[166:167], 0, s[4:5]
	s_waitcnt lgkmcnt(0)
	v_add_f32_e32 v80, v80, v106
	global_atomic_add_f32 v[108:109], v80, off offset:64

.LBB0_372:
	v_xor_b32_e32 v80, 16, v195
	v_cmp_lt_i32_e32 vcc, v80, v197
	s_nop 1
	v_cndmask_b32_e32 v80, v195, v80, vcc
	v_lshlrev_b32_e32 v80, 2, v80
	v_mov_b32_e32 v80, v139
	s_nop 1
	v_permlane32_swap_b32 v80, v139
	s_nop 1
	v_cmp_lt_i32_e32 vcc, v196, v197
	s_waitcnt lgkmcnt(0)
	v_add_f32_e32 v80, v139, v80
	v_cndmask_b32_e32 v98, v195, v196, vcc
	v_lshlrev_b32_e32 v98, 2, v98
	v_mov_b32_e32 v98, v80
	s_nop 1
	v_permlane16_swap_b32 v98, v80
	s_nop 1
	s_and_saveexec_b64 s[60:61], s[46:47]
	s_cbranch_execz .LBB0_374
	s_cmp_lt_u32 s43, 7
	s_cselect_b32 s4, s16, 0xa0000
	v_lshl_add_u64 v[100:101], v[166:167], 0, s[4:5]
	s_waitcnt lgkmcnt(0)
	v_add_f32_e32 v80, v80, v98
	global_atomic_add_f32 v[100:101], v80, off offset:64

.LBB0_392:
	v_xor_b32_e32 v80, 16, v195
	v_cmp_lt_i32_e32 vcc, v80, v197
	s_nop 1
	v_cndmask_b32_e32 v80, v195, v80, vcc
	v_lshlrev_b32_e32 v80, 2, v80
	v_mov_b32_e32 v80, v119
	s_nop 1
	v_permlane32_swap_b32 v80, v119
	s_nop 1
	v_cmp_lt_i32_e32 vcc, v196, v197
	s_waitcnt lgkmcnt(0)
	v_add_f32_e32 v80, v119, v80
	v_cndmask_b32_e32 v90, v195, v196, vcc
	v_lshlrev_b32_e32 v90, 2, v90
	v_mov_b32_e32 v90, v80
	s_nop 1
	v_permlane16_swap_b32 v90, v80
	s_nop 1
	s_and_saveexec_b64 s[60:61], s[46:47]
	s_cbranch_execz .LBB0_394
	s_cmp_lt_u32 s11, 7
	s_cselect_b32 s4, s16, 0xa0000
	v_lshl_add_u64 v[92:93], v[166:167], 0, s[4:5]
	s_waitcnt lgkmcnt(0)
	v_add_f32_e32 v80, v80, v90
	global_atomic_add_f32 v[92:93], v80, off offset:128

.LBB0_412:
	v_xor_b32_e32 v80, 16, v195
	v_cmp_lt_i32_e32 vcc, v80, v197
	s_nop 1
	v_cndmask_b32_e32 v80, v195, v80, vcc
	v_lshlrev_b32_e32 v80, 2, v80
	v_mov_b32_e32 v80, v118
	s_nop 1
	v_permlane32_swap_b32 v80, v118
	s_nop 1
	v_cmp_lt_i32_e32 vcc, v196, v197
	s_waitcnt lgkmcnt(0)
	v_add_f32_e32 v80, v118, v80
	v_cndmask_b32_e32 v82, v195, v196, vcc
	v_lshlrev_b32_e32 v82, 2, v82
	v_mov_b32_e32 v82, v80
	s_nop 1
	v_permlane16_swap_b32 v82, v80
	s_nop 1
	s_and_saveexec_b64 s[60:61], s[46:47]
	s_cbranch_execz .LBB0_414
	s_cmp_lt_u32 s43, 7
	s_cselect_b32 s4, s16, 0xa0000
	v_lshl_add_u64 v[84:85], v[166:167], 0, s[4:5]
	s_waitcnt lgkmcnt(0)
	v_add_f32_e32 v80, v80, v82
	global_atomic_add_f32 v[84:85], v80, off offset:128

.LBB0_431:
	s_and_b64 vcc, exec, s[54:55]
	s_cbranch_vccnz .LBB0_435
	v_xor_b32_e32 v72, 16, v195
	v_cmp_lt_i32_e32 vcc, v72, v197
	s_nop 1
	v_cndmask_b32_e32 v72, v195, v72, vcc
	v_lshlrev_b32_e32 v72, 2, v72
	v_mov_b32_e32 v72, v103
	s_nop 1
	v_permlane32_swap_b32 v72, v103
	s_nop 1
	v_cmp_lt_i32_e32 vcc, v196, v197
	s_waitcnt lgkmcnt(0)
	v_add_f32_e32 v72, v103, v72
	v_cndmask_b32_e32 v73, v195, v196, vcc
	v_lshlrev_b32_e32 v73, 2, v73
	v_mov_b32_e32 v73, v72
	s_nop 1
	v_permlane16_swap_b32 v73, v72
	s_nop 1
	s_and_saveexec_b64 s[60:61], s[46:47]
	s_cbranch_execz .LBB0_434
	s_cmp_lt_u32 s11, 7
	s_cselect_b32 s4, s16, 0xa0000
	v_lshl_add_u64 v[74:75], v[166:167], 0, s[4:5]
	s_waitcnt lgkmcnt(0)
	v_add_f32_e32 v72, v72, v73
	global_atomic_add_f32 v[74:75], v72, off offset:192

.LBB0_452:
	v_xor_b32_e32 v64, 16, v195
	v_cmp_lt_i32_e32 vcc, v64, v197
	s_nop 1
	v_cndmask_b32_e32 v64, v195, v64, vcc
	v_lshlrev_b32_e32 v64, 2, v64
	v_mov_b32_e32 v64, v102
	s_nop 1
	v_permlane32_swap_b32 v64, v102
	s_nop 1
	v_cmp_lt_i32_e32 vcc, v196, v197
	s_waitcnt lgkmcnt(0)
	v_add_f32_e32 v64, v102, v64
	v_cndmask_b32_e32 v65, v195, v196, vcc
	v_lshlrev_b32_e32 v65, 2, v65
	v_mov_b32_e32 v65, v64
	s_nop 1
	v_permlane16_swap_b32 v65, v64
	s_nop 1
	s_and_saveexec_b64 s[60:61], s[46:47]
	s_cbranch_execz .LBB0_454
	s_cmp_lt_u32 s43, 7
	s_cselect_b32 s4, s16, 0xa0000
	v_lshl_add_u64 v[66:67], v[166:167], 0, s[4:5]
	s_waitcnt lgkmcnt(0)
	v_add_f32_e32 v64, v64, v65
	global_atomic_add_f32 v[66:67], v64, off offset:192

.LBB0_472:
	v_xor_b32_e32 v56, 16, v195
	v_cmp_lt_i32_e32 vcc, v56, v197
	s_nop 1
	v_cndmask_b32_e32 v56, v195, v56, vcc
	v_lshlrev_b32_e32 v56, 2, v56
	v_mov_b32_e32 v56, v89
	s_nop 1
	v_permlane32_swap_b32 v56, v89
	s_nop 1
	v_cmp_lt_i32_e32 vcc, v196, v197
	s_waitcnt lgkmcnt(0)
	v_add_f32_e32 v56, v89, v56
	v_cndmask_b32_e32 v57, v195, v196, vcc
	v_lshlrev_b32_e32 v57, 2, v57
	v_mov_b32_e32 v57, v56
	s_nop 1
	v_permlane16_swap_b32 v57, v56
	s_nop 1
	s_and_saveexec_b64 s[60:61], s[46:47]
	s_cbranch_execz .LBB0_474
	s_cmp_lt_u32 s11, 7
	s_cselect_b32 s4, s16, 0xa0000
	v_lshl_add_u64 v[58:59], v[76:77], 0, s[4:5]
	s_waitcnt lgkmcnt(0)
	v_add_f32_e32 v56, v56, v57
	global_atomic_add_f32 v[58:59], v56, off

.LBB0_492:
	v_xor_b32_e32 v48, 16, v195
	v_cmp_lt_i32_e32 vcc, v48, v197
	s_nop 1
	v_cndmask_b32_e32 v48, v195, v48, vcc
	v_lshlrev_b32_e32 v48, 2, v48
	v_mov_b32_e32 v48, v88
	s_nop 1
	v_permlane32_swap_b32 v48, v88
	s_nop 1
	v_cmp_lt_i32_e32 vcc, v196, v197
	s_waitcnt lgkmcnt(0)
	v_add_f32_e32 v48, v88, v48
	v_cndmask_b32_e32 v49, v195, v196, vcc
	v_lshlrev_b32_e32 v49, 2, v49
	v_mov_b32_e32 v49, v48
	s_nop 1
	v_permlane16_swap_b32 v49, v48
	s_nop 1
	s_and_saveexec_b64 s[60:61], s[46:47]
	s_cbranch_execz .LBB0_494
	s_cmp_lt_u32 s43, 7
	s_cselect_b32 s4, s16, 0xa0000
	v_lshl_add_u64 v[50:51], v[76:77], 0, s[4:5]
	s_waitcnt lgkmcnt(0)
	v_add_f32_e32 v48, v48, v49
	global_atomic_add_f32 v[50:51], v48, off

.LBB0_511:
	s_and_b64 vcc, exec, s[54:55]
	s_cbranch_vccnz .LBB0_515
	v_xor_b32_e32 v40, 16, v195
	v_cmp_lt_i32_e32 vcc, v40, v197
	s_nop 1
	v_cndmask_b32_e32 v40, v195, v40, vcc
	v_lshlrev_b32_e32 v40, 2, v40
	v_mov_b32_e32 v40, v71
	s_nop 1
	v_permlane32_swap_b32 v40, v71
	s_nop 1
	v_cmp_lt_i32_e32 vcc, v196, v197
	s_waitcnt lgkmcnt(0)
	v_add_f32_e32 v40, v71, v40
	v_cndmask_b32_e32 v41, v195, v196, vcc
	v_lshlrev_b32_e32 v41, 2, v41
	v_mov_b32_e32 v41, v40
	s_nop 1
	v_permlane16_swap_b32 v41, v40
	s_nop 1
	s_and_saveexec_b64 s[60:61], s[46:47]
	s_cbranch_execz .LBB0_514
	s_cmp_lt_u32 s11, 7
	s_cselect_b32 s4, s16, 0xa0000
	v_lshl_add_u64 v[42:43], v[60:61], 0, s[4:5]
	s_waitcnt lgkmcnt(0)
	v_add_f32_e32 v40, v40, v41
	global_atomic_add_f32 v[42:43], v40, off

.LBB0_532:
	v_xor_b32_e32 v32, 16, v195
	v_cmp_lt_i32_e32 vcc, v32, v197
	s_nop 1
	v_cndmask_b32_e32 v32, v195, v32, vcc
	v_lshlrev_b32_e32 v32, 2, v32
	v_mov_b32_e32 v32, v72
	s_nop 1
	v_permlane32_swap_b32 v32, v72
	s_nop 1
	v_cmp_lt_i32_e32 vcc, v196, v197
	s_waitcnt lgkmcnt(0)
	v_add_f32_e32 v32, v72, v32
	v_cndmask_b32_e32 v33, v195, v196, vcc
	v_lshlrev_b32_e32 v33, 2, v33
	v_mov_b32_e32 v33, v32
	s_nop 1
	v_permlane16_swap_b32 v33, v32
	s_nop 1
	s_and_saveexec_b64 s[60:61], s[46:47]
	s_cbranch_execz .LBB0_534
	s_cmp_lt_u32 s43, 7
	s_cselect_b32 s4, s16, 0xa0000
	v_lshl_add_u64 v[34:35], v[60:61], 0, s[4:5]
	s_waitcnt lgkmcnt(0)
	v_add_f32_e32 v32, v32, v33
	global_atomic_add_f32 v[34:35], v32, off

.LBB0_552:
	v_xor_b32_e32 v24, 16, v195
	v_cmp_lt_i32_e32 vcc, v24, v197
	s_nop 1
	v_cndmask_b32_e32 v24, v195, v24, vcc
	v_lshlrev_b32_e32 v24, 2, v24
	v_mov_b32_e32 v24, v55
	s_nop 1
	v_permlane32_swap_b32 v24, v55
	s_nop 1
	v_cmp_lt_i32_e32 vcc, v196, v197
	s_waitcnt lgkmcnt(0)
	v_add_f32_e32 v24, v55, v24
	v_cndmask_b32_e32 v25, v195, v196, vcc
	v_lshlrev_b32_e32 v25, 2, v25
	v_mov_b32_e32 v25, v24
	s_nop 1
	v_permlane16_swap_b32 v25, v24
	s_nop 1
	s_and_saveexec_b64 s[60:61], s[46:47]
	s_cbranch_execz .LBB0_554
	s_cmp_lt_u32 s11, 7
	s_cselect_b32 s4, s16, 0xa0000
	v_lshl_add_u64 v[26:27], v[44:45], 0, s[4:5]
	s_waitcnt lgkmcnt(0)
	v_add_f32_e32 v24, v24, v25
	global_atomic_add_f32 v[26:27], v24, off

.LBB0_572:
	v_xor_b32_e32 v16, 16, v195
	v_cmp_lt_i32_e32 vcc, v16, v197
	s_nop 1
	v_cndmask_b32_e32 v16, v195, v16, vcc
	v_lshlrev_b32_e32 v16, 2, v16
	v_mov_b32_e32 v16, v54
	s_nop 1
	v_permlane32_swap_b32 v16, v54
	s_nop 1
	v_cmp_lt_i32_e32 vcc, v196, v197
	s_waitcnt lgkmcnt(0)
	v_add_f32_e32 v16, v54, v16
	v_cndmask_b32_e32 v17, v195, v196, vcc
	v_lshlrev_b32_e32 v17, 2, v17
	v_mov_b32_e32 v17, v16
	s_nop 1
	v_permlane16_swap_b32 v17, v16
	s_nop 1
	s_and_saveexec_b64 s[60:61], s[46:47]
	s_cbranch_execz .LBB0_574
	s_cmp_lt_u32 s43, 7
	s_cselect_b32 s4, s16, 0xa0000
	v_lshl_add_u64 v[18:19], v[44:45], 0, s[4:5]
	s_waitcnt lgkmcnt(0)
	v_add_f32_e32 v16, v16, v17
	global_atomic_add_f32 v[18:19], v16, off

.LBB0_591:
	s_and_b64 vcc, exec, s[54:55]
	s_cbranch_vccnz .LBB0_595
	v_xor_b32_e32 v8, 16, v195
	v_cmp_lt_i32_e32 vcc, v8, v197
	s_nop 1
	v_cndmask_b32_e32 v8, v195, v8, vcc
	v_lshlrev_b32_e32 v8, 2, v8
	v_mov_b32_e32 v8, v37
	s_nop 1
	v_permlane32_swap_b32 v8, v37
	s_nop 1
	v_cmp_lt_i32_e32 vcc, v196, v197
	s_waitcnt lgkmcnt(0)
	v_add_f32_e32 v8, v37, v8
	v_cndmask_b32_e32 v9, v195, v196, vcc
	v_lshlrev_b32_e32 v9, 2, v9
	v_mov_b32_e32 v9, v8
	s_nop 1
	v_permlane16_swap_b32 v9, v8
	s_nop 1
	s_and_saveexec_b64 s[54:55], s[46:47]
	s_cbranch_execz .LBB0_594
	s_cmp_lt_u32 s11, 7
	s_cselect_b32 s4, s16, 0xa0000
	v_lshl_add_u64 v[10:11], v[28:29], 0, s[4:5]
	s_waitcnt lgkmcnt(0)
	v_add_f32_e32 v8, v8, v9
	global_atomic_add_f32 v[10:11], v8, off

.LBB0_645:
	s_or_b64 exec, exec, s[44:45]
	v_or_b32_e32 v116, 16, v142
	v_ashrrev_i32_e32 v117, 31, v116
	s_waitcnt lgkmcnt(0)
	v_lshlrev_b64 v[114:115], 11, v[116:117]
	v_lshl_add_u64 v[114:115], s[38:39], 0, v[114:115]
	v_lshlrev_b32_e32 v119, 3, v147
	v_lshl_add_u64 v[114:115], s[42:43], 1, v[114:115]
	v_lshl_add_u64 v[120:121], v[114:115], 0, v[80:81]
	v_lshlrev_b32_e32 v114, 1, v119
	v_mov_b32_e32 v115, v81
	v_lshl_add_u64 v[128:129], v[120:121], 0, v[114:115]
	s_waitcnt vmcnt(14)
	v_lshlrev_b32_e32 v148, 16, v176
	v_and_b32_e32 v149, 0xffff0000, v176
	v_pk_fma_f32 v[110:111], v[110:111], 0.5, v[148:149] op_sel_hi:[1,0,1]
	v_lshlrev_b32_e32 v120, 16, v177
	v_and_b32_e32 v121, 0xffff0000, v177
	v_lshlrev_b32_e32 v150, 16, v178
	v_and_b32_e32 v151, 0xffff0000, v178
	v_lshlrev_b32_e32 v122, 16, v179
	v_and_b32_e32 v123, 0xffff0000, v179
	v_mul_f32_e32 v119, v111, v111
	v_pk_fma_f32 v[112:113], v[112:113], 0.5, v[120:121] op_sel_hi:[1,0,1]
	v_pk_fma_f32 v[120:121], v[108:109], 0.5, v[122:123] op_sel_hi:[1,0,1]
	v_pk_fma_f32 v[122:123], v[106:107], 0.5, v[150:151] op_sel_hi:[1,0,1]
	v_cvt_pk_bf16_f32 v106, v110, v111
	v_cvt_pk_bf16_f32 v107, v112, v113
	v_fmac_f32_e32 v119, v110, v110
	v_cvt_pk_bf16_f32 v108, v122, v123
	v_cvt_pk_bf16_f32 v109, v120, v121
	global_store_dwordx4 v[128:129], v[106:109], off
	v_fmac_f32_e32 v119, v112, v112
	v_lshlrev_b32_e32 v110, 16, v182
	v_lshlrev_b32_e32 v106, 16, v180
	v_and_b32_e32 v107, 0xffff0000, v180
	v_lshlrev_b32_e32 v108, 16, v181
	v_and_b32_e32 v109, 0xffff0000, v181
	v_and_b32_e32 v111, 0xffff0000, v182
	v_fmac_f32_e32 v119, v113, v113
	v_lshlrev_b32_e32 v112, 16, v183
	v_and_b32_e32 v113, 0xffff0000, v183
	v_pk_fma_f32 v[104:105], v[104:105], 0.5, v[108:109] op_sel_hi:[1,0,1]
	v_pk_fma_f32 v[102:103], v[102:103], 0.5, v[106:107] op_sel_hi:[1,0,1]
	v_pk_fma_f32 v[108:109], v[98:99], 0.5, v[110:111] op_sel_hi:[1,0,1]
	v_cvt_pk_bf16_f32 v98, v102, v103
	v_pk_fma_f32 v[106:107], v[100:101], 0.5, v[112:113] op_sel_hi:[1,0,1]
	v_cvt_pk_bf16_f32 v99, v104, v105
	v_cvt_pk_bf16_f32 v100, v108, v109
	v_fmac_f32_e32 v119, v122, v122
	v_cvt_pk_bf16_f32 v101, v106, v107
	global_store_dwordx4 v[128:129], v[98:101], off offset:256
	v_fmac_f32_e32 v119, v123, v123
	v_fmac_f32_e32 v119, v120, v120
	v_mul_f32_e32 v98, v103, v103
	v_fmac_f32_e32 v98, v102, v102
	v_fmac_f32_e32 v98, v104, v104
	v_fmac_f32_e32 v98, v105, v105
	v_fmac_f32_e32 v98, v108, v108
	v_fmac_f32_e32 v98, v109, v109
	v_fmac_f32_e32 v98, v106, v106
	v_fmac_f32_e32 v119, v121, v121
	v_fmac_f32_e32 v98, v107, v107
	v_add_f32_e32 v98, v119, v98
	v_mov_b32_e32 v99, v98
	s_nop 1
	v_permlane32_swap_b32 v99, v98
	s_nop 1
	s_waitcnt lgkmcnt(0)
	v_add_f32_e32 v98, v98, v99
	v_mov_b32_e32 v99, v98
	s_nop 1
	v_permlane16_swap_b32 v99, v98
	s_nop 1
	s_and_saveexec_b64 s[44:45], vcc
	s_cbranch_execz .LBB0_647
	v_lshl_add_u64 v[100:101], v[116:117], 2, s[26:27]
	s_waitcnt lgkmcnt(0)
	v_add_f32_e32 v98, v98, v99
	global_atomic_add_f32 v[100:101], v98, off
.LBB0_647:
	s_or_b64 exec, exec, s[44:45]
	v_or_b32_e32 v98, 32, v142
	s_waitcnt lgkmcnt(0)
	v_ashrrev_i32_e32 v99, 31, v98
	v_lshlrev_b64 v[100:101], 11, v[98:99]
	v_lshl_add_u64 v[100:101], s[38:39], 0, v[100:101]
	v_lshl_add_u64 v[100:101], s[42:43], 1, v[100:101]
	v_lshl_add_u64 v[100:101], v[100:101], 0, v[80:81]
	v_lshl_add_u64 v[108:109], v[100:101], 0, v[114:115]
	s_waitcnt vmcnt(14)
	v_lshlrev_b32_e32 v110, 16, v184
	v_and_b32_e32 v111, 0xffff0000, v184
	v_pk_fma_f32 v[94:95], v[94:95], 0.5, v[110:111] op_sel_hi:[1,0,1]
	v_lshlrev_b32_e32 v100, 16, v185
	v_and_b32_e32 v101, 0xffff0000, v185
	v_lshlrev_b32_e32 v112, 16, v186
	v_and_b32_e32 v113, 0xffff0000, v186
	v_lshlrev_b32_e32 v102, 16, v187
	v_and_b32_e32 v103, 0xffff0000, v187
	v_mul_f32_e32 v110, v95, v95
	v_pk_fma_f32 v[96:97], v[96:97], 0.5, v[100:101] op_sel_hi:[1,0,1]
	v_pk_fma_f32 v[100:101], v[92:93], 0.5, v[102:103] op_sel_hi:[1,0,1]
	v_pk_fma_f32 v[102:103], v[90:91], 0.5, v[112:113] op_sel_hi:[1,0,1]
	v_cvt_pk_bf16_f32 v90, v94, v95
	v_cvt_pk_bf16_f32 v91, v96, v97
	v_fmac_f32_e32 v110, v94, v94
	v_cvt_pk_bf16_f32 v92, v102, v103
	v_cvt_pk_bf16_f32 v93, v100, v101
	global_store_dwordx4 v[108:109], v[90:93], off
	v_fmac_f32_e32 v110, v96, v96
	v_lshlrev_b32_e32 v94, 16, v190
	v_lshlrev_b32_e32 v90, 16, v188
	v_and_b32_e32 v91, 0xffff0000, v188
	v_lshlrev_b32_e32 v92, 16, v189
	v_and_b32_e32 v93, 0xffff0000, v189
	v_and_b32_e32 v95, 0xffff0000, v190
	v_fmac_f32_e32 v110, v97, v97
	v_lshlrev_b32_e32 v96, 16, v191
	v_and_b32_e32 v97, 0xffff0000, v191
	v_pk_fma_f32 v[88:89], v[88:89], 0.5, v[92:93] op_sel_hi:[1,0,1]
	v_pk_fma_f32 v[86:87], v[86:87], 0.5, v[90:91] op_sel_hi:[1,0,1]
	v_pk_fma_f32 v[92:93], v[82:83], 0.5, v[94:95] op_sel_hi:[1,0,1]
	v_cvt_pk_bf16_f32 v82, v86, v87
	v_pk_fma_f32 v[90:91], v[84:85], 0.5, v[96:97] op_sel_hi:[1,0,1]
	v_cvt_pk_bf16_f32 v83, v88, v89
	v_cvt_pk_bf16_f32 v84, v92, v93
	v_fmac_f32_e32 v110, v102, v102
	v_cvt_pk_bf16_f32 v85, v90, v91
	global_store_dwordx4 v[108:109], v[82:85], off offset:256
	v_fmac_f32_e32 v110, v103, v103
	v_fmac_f32_e32 v110, v100, v100
	v_mul_f32_e32 v82, v87, v87
	v_fmac_f32_e32 v82, v86, v86
	v_fmac_f32_e32 v82, v88, v88
	v_fmac_f32_e32 v82, v89, v89
	v_fmac_f32_e32 v82, v92, v92
	v_fmac_f32_e32 v82, v93, v93
	v_fmac_f32_e32 v82, v90, v90
	v_fmac_f32_e32 v110, v101, v101
	v_fmac_f32_e32 v82, v91, v91
	v_add_f32_e32 v82, v110, v82
	v_mov_b32_e32 v83, v82
	s_nop 1
	v_permlane32_swap_b32 v83, v82
	s_nop 1
	s_waitcnt lgkmcnt(0)
	v_add_f32_e32 v82, v82, v83
	v_mov_b32_e32 v83, v82
	s_nop 1
	v_permlane16_swap_b32 v83, v82
	s_nop 1
	s_and_saveexec_b64 s[44:45], vcc
	s_cbranch_execz .LBB0_649
	v_lshl_add_u64 v[84:85], v[98:99], 2, s[26:27]
	s_waitcnt lgkmcnt(0)
	v_add_f32_e32 v82, v82, v83
	global_atomic_add_f32 v[84:85], v82, off
.LBB0_649:
	s_or_b64 exec, exec, s[44:45]
	v_or_b32_e32 v82, 48, v142
	s_waitcnt lgkmcnt(0)
	v_ashrrev_i32_e32 v83, 31, v82
	v_lshlrev_b64 v[84:85], 11, v[82:83]
	v_lshl_add_u64 v[84:85], s[38:39], 0, v[84:85]
	v_lshl_add_u64 v[84:85], s[42:43], 1, v[84:85]
	v_lshl_add_u64 v[84:85], v[84:85], 0, v[80:81]
	v_mov_b32_e32 v115, v81
	v_lshl_add_u64 v[92:93], v[84:85], 0, v[114:115]
	s_waitcnt vmcnt(14)
	v_lshlrev_b32_e32 v94, 16, v204
	v_and_b32_e32 v95, 0xffff0000, v204
	v_pk_fma_f32 v[76:77], v[76:77], 0.5, v[94:95] op_sel_hi:[1,0,1]
	v_lshlrev_b32_e32 v84, 16, v205
	v_and_b32_e32 v85, 0xffff0000, v205
	v_lshlrev_b32_e32 v96, 16, v206
	v_and_b32_e32 v97, 0xffff0000, v206
	v_lshlrev_b32_e32 v86, 16, v207
	v_and_b32_e32 v87, 0xffff0000, v207
	v_mul_f32_e32 v94, v77, v77
	v_pk_fma_f32 v[78:79], v[78:79], 0.5, v[84:85] op_sel_hi:[1,0,1]
	v_pk_fma_f32 v[84:85], v[74:75], 0.5, v[86:87] op_sel_hi:[1,0,1]
	v_pk_fma_f32 v[86:87], v[72:73], 0.5, v[96:97] op_sel_hi:[1,0,1]
	v_cvt_pk_bf16_f32 v72, v76, v77
	v_cvt_pk_bf16_f32 v73, v78, v79
	v_fmac_f32_e32 v94, v76, v76
	v_cvt_pk_bf16_f32 v74, v86, v87
	v_cvt_pk_bf16_f32 v75, v84, v85
	global_store_dwordx4 v[92:93], v[72:75], off
	v_fmac_f32_e32 v94, v78, v78
	v_lshlrev_b32_e32 v76, 16, v210
	v_lshlrev_b32_e32 v72, 16, v208
	v_and_b32_e32 v73, 0xffff0000, v208
	v_lshlrev_b32_e32 v74, 16, v209
	v_and_b32_e32 v75, 0xffff0000, v209
	v_and_b32_e32 v77, 0xffff0000, v210
	v_fmac_f32_e32 v94, v79, v79
	v_lshlrev_b32_e32 v78, 16, v211
	v_and_b32_e32 v79, 0xffff0000, v211
	v_pk_fma_f32 v[70:71], v[70:71], 0.5, v[74:75] op_sel_hi:[1,0,1]
	v_pk_fma_f32 v[68:69], v[68:69], 0.5, v[72:73] op_sel_hi:[1,0,1]
	v_pk_fma_f32 v[74:75], v[64:65], 0.5, v[76:77] op_sel_hi:[1,0,1]
	v_cvt_pk_bf16_f32 v64, v68, v69
	v_pk_fma_f32 v[72:73], v[66:67], 0.5, v[78:79] op_sel_hi:[1,0,1]
	v_cvt_pk_bf16_f32 v65, v70, v71
	v_cvt_pk_bf16_f32 v66, v74, v75
	v_fmac_f32_e32 v94, v86, v86
	v_cvt_pk_bf16_f32 v67, v72, v73
	global_store_dwordx4 v[92:93], v[64:67], off offset:256
	v_fmac_f32_e32 v94, v87, v87
	v_fmac_f32_e32 v94, v84, v84
	v_mul_f32_e32 v64, v69, v69
	v_fmac_f32_e32 v64, v68, v68
	v_fmac_f32_e32 v64, v70, v70
	v_fmac_f32_e32 v64, v71, v71
	v_fmac_f32_e32 v64, v74, v74
	v_fmac_f32_e32 v64, v75, v75
	v_fmac_f32_e32 v64, v72, v72
	v_fmac_f32_e32 v94, v85, v85
	v_fmac_f32_e32 v64, v73, v73
	v_add_f32_e32 v64, v94, v64
	v_mov_b32_e32 v65, v64
	s_nop 1
	v_permlane32_swap_b32 v65, v64
	s_nop 1
	s_waitcnt lgkmcnt(0)
	v_add_f32_e32 v64, v64, v65
	v_mov_b32_e32 v65, v64
	s_nop 1
	v_permlane16_swap_b32 v65, v64
	s_nop 1
	s_and_saveexec_b64 s[44:45], vcc
	s_cbranch_execz .LBB0_651
	v_lshl_add_u64 v[66:67], v[82:83], 2, s[26:27]
	s_waitcnt lgkmcnt(0)
	v_add_f32_e32 v64, v64, v65
	global_atomic_add_f32 v[66:67], v64, off
.LBB0_651:
	s_or_b64 exec, exec, s[44:45]
	v_add_u32_e32 v64, 0x80, v142
	s_waitcnt lgkmcnt(0)
	v_ashrrev_i32_e32 v65, 31, v64
	v_lshlrev_b64 v[66:67], 11, v[64:65]
	v_lshl_add_u64 v[66:67], s[38:39], 0, v[66:67]
	v_lshl_add_u64 v[66:67], s[42:43], 1, v[66:67]
	v_lshl_add_u64 v[66:67], v[66:67], 0, v[80:81]
	v_lshl_add_u64 v[74:75], v[66:67], 0, v[114:115]
	s_waitcnt vmcnt(14)
	v_lshlrev_b32_e32 v76, 16, v212
	v_and_b32_e32 v77, 0xffff0000, v212
	v_pk_fma_f32 v[60:61], v[60:61], 0.5, v[76:77] op_sel_hi:[1,0,1]
	v_lshlrev_b32_e32 v66, 16, v213
	v_and_b32_e32 v67, 0xffff0000, v213
	v_lshlrev_b32_e32 v78, 16, v214
	v_and_b32_e32 v79, 0xffff0000, v214
	v_lshlrev_b32_e32 v68, 16, v215
	v_and_b32_e32 v69, 0xffff0000, v215
	v_mul_f32_e32 v76, v61, v61
	v_pk_fma_f32 v[62:63], v[62:63], 0.5, v[66:67] op_sel_hi:[1,0,1]
	v_pk_fma_f32 v[66:67], v[58:59], 0.5, v[68:69] op_sel_hi:[1,0,1]
	v_pk_fma_f32 v[68:69], v[56:57], 0.5, v[78:79] op_sel_hi:[1,0,1]
	v_cvt_pk_bf16_f32 v56, v60, v61
	v_cvt_pk_bf16_f32 v57, v62, v63
	v_fmac_f32_e32 v76, v60, v60
	v_cvt_pk_bf16_f32 v58, v68, v69
	v_cvt_pk_bf16_f32 v59, v66, v67
	global_store_dwordx4 v[74:75], v[56:59], off
	v_fmac_f32_e32 v76, v62, v62
	v_lshlrev_b32_e32 v60, 16, v218
	v_lshlrev_b32_e32 v56, 16, v216
	v_and_b32_e32 v57, 0xffff0000, v216
	v_lshlrev_b32_e32 v58, 16, v217
	v_and_b32_e32 v59, 0xffff0000, v217
	v_and_b32_e32 v61, 0xffff0000, v218
	v_fmac_f32_e32 v76, v63, v63
	v_lshlrev_b32_e32 v62, 16, v219
	v_and_b32_e32 v63, 0xffff0000, v219
	v_pk_fma_f32 v[54:55], v[54:55], 0.5, v[58:59] op_sel_hi:[1,0,1]
	v_pk_fma_f32 v[52:53], v[52:53], 0.5, v[56:57] op_sel_hi:[1,0,1]
	v_pk_fma_f32 v[58:59], v[48:49], 0.5, v[60:61] op_sel_hi:[1,0,1]
	v_cvt_pk_bf16_f32 v48, v52, v53
	v_pk_fma_f32 v[56:57], v[50:51], 0.5, v[62:63] op_sel_hi:[1,0,1]
	v_cvt_pk_bf16_f32 v49, v54, v55
	v_cvt_pk_bf16_f32 v50, v58, v59
	v_fmac_f32_e32 v76, v68, v68
	v_cvt_pk_bf16_f32 v51, v56, v57
	global_store_dwordx4 v[74:75], v[48:51], off offset:256
	v_fmac_f32_e32 v76, v69, v69
	v_fmac_f32_e32 v76, v66, v66
	v_mul_f32_e32 v48, v53, v53
	v_fmac_f32_e32 v48, v52, v52
	v_fmac_f32_e32 v48, v54, v54
	v_fmac_f32_e32 v48, v55, v55
	v_fmac_f32_e32 v48, v58, v58
	v_fmac_f32_e32 v48, v59, v59
	v_fmac_f32_e32 v48, v56, v56
	v_fmac_f32_e32 v76, v67, v67
	v_fmac_f32_e32 v48, v57, v57
	v_add_f32_e32 v48, v76, v48
	v_mov_b32_e32 v49, v48
	s_nop 1
	v_permlane32_swap_b32 v49, v48
	s_nop 1
	s_waitcnt lgkmcnt(0)
	v_add_f32_e32 v48, v48, v49
	v_mov_b32_e32 v49, v48
	s_nop 1
	v_permlane16_swap_b32 v49, v48
	s_nop 1
	s_and_saveexec_b64 s[44:45], vcc
	s_cbranch_execz .LBB0_653
	v_lshl_add_u64 v[50:51], v[64:65], 2, s[26:27]
	s_waitcnt lgkmcnt(0)
	v_add_f32_e32 v48, v48, v49
	global_atomic_add_f32 v[50:51], v48, off
.LBB0_653:
	s_or_b64 exec, exec, s[44:45]
	v_add_u32_e32 v48, 0x90, v142
	s_waitcnt lgkmcnt(0)
	v_ashrrev_i32_e32 v49, 31, v48
	v_lshlrev_b64 v[50:51], 11, v[48:49]
	v_lshl_add_u64 v[50:51], s[38:39], 0, v[50:51]
	v_lshl_add_u64 v[50:51], s[42:43], 1, v[50:51]
	v_lshl_add_u64 v[50:51], v[50:51], 0, v[80:81]
	v_mov_b32_e32 v115, v81
	v_lshl_add_u64 v[58:59], v[50:51], 0, v[114:115]
	s_waitcnt vmcnt(14)
	v_lshlrev_b32_e32 v60, 16, v220
	v_and_b32_e32 v61, 0xffff0000, v220
	v_pk_fma_f32 v[44:45], v[44:45], 0.5, v[60:61] op_sel_hi:[1,0,1]
	v_lshlrev_b32_e32 v50, 16, v221
	v_and_b32_e32 v51, 0xffff0000, v221
	v_lshlrev_b32_e32 v62, 16, v222
	v_and_b32_e32 v63, 0xffff0000, v222
	v_lshlrev_b32_e32 v52, 16, v223
	v_and_b32_e32 v53, 0xffff0000, v223
	v_mul_f32_e32 v60, v45, v45
	v_pk_fma_f32 v[46:47], v[46:47], 0.5, v[50:51] op_sel_hi:[1,0,1]
	v_pk_fma_f32 v[50:51], v[42:43], 0.5, v[52:53] op_sel_hi:[1,0,1]
	v_pk_fma_f32 v[52:53], v[40:41], 0.5, v[62:63] op_sel_hi:[1,0,1]
	v_cvt_pk_bf16_f32 v40, v44, v45
	v_cvt_pk_bf16_f32 v41, v46, v47
	v_fmac_f32_e32 v60, v44, v44
	v_cvt_pk_bf16_f32 v42, v52, v53
	v_cvt_pk_bf16_f32 v43, v50, v51
	global_store_dwordx4 v[58:59], v[40:43], off
	v_fmac_f32_e32 v60, v46, v46
	v_lshlrev_b32_e32 v44, 16, v226
	v_lshlrev_b32_e32 v40, 16, v224
	v_and_b32_e32 v41, 0xffff0000, v224
	v_lshlrev_b32_e32 v42, 16, v225
	v_and_b32_e32 v43, 0xffff0000, v225
	v_and_b32_e32 v45, 0xffff0000, v226
	v_fmac_f32_e32 v60, v47, v47
	v_lshlrev_b32_e32 v46, 16, v227
	v_and_b32_e32 v47, 0xffff0000, v227
	v_pk_fma_f32 v[38:39], v[38:39], 0.5, v[42:43] op_sel_hi:[1,0,1]
	v_pk_fma_f32 v[36:37], v[36:37], 0.5, v[40:41] op_sel_hi:[1,0,1]
	v_pk_fma_f32 v[42:43], v[32:33], 0.5, v[44:45] op_sel_hi:[1,0,1]
	v_cvt_pk_bf16_f32 v32, v36, v37
	v_pk_fma_f32 v[40:41], v[34:35], 0.5, v[46:47] op_sel_hi:[1,0,1]
	v_cvt_pk_bf16_f32 v33, v38, v39
	v_cvt_pk_bf16_f32 v34, v42, v43
	v_fmac_f32_e32 v60, v52, v52
	v_cvt_pk_bf16_f32 v35, v40, v41
	global_store_dwordx4 v[58:59], v[32:35], off offset:256
	v_fmac_f32_e32 v60, v53, v53
	v_fmac_f32_e32 v60, v50, v50
	v_mul_f32_e32 v32, v37, v37
	v_fmac_f32_e32 v32, v36, v36
	v_fmac_f32_e32 v32, v38, v38
	v_fmac_f32_e32 v32, v39, v39
	v_fmac_f32_e32 v32, v42, v42
	v_fmac_f32_e32 v32, v43, v43
	v_fmac_f32_e32 v32, v40, v40
	v_fmac_f32_e32 v60, v51, v51
	v_fmac_f32_e32 v32, v41, v41
	v_add_f32_e32 v32, v60, v32
	v_mov_b32_e32 v33, v32
	s_nop 1
	v_permlane32_swap_b32 v33, v32
	s_nop 1
	s_waitcnt lgkmcnt(0)
	v_add_f32_e32 v32, v32, v33
	v_mov_b32_e32 v33, v32
	s_nop 1
	v_permlane16_swap_b32 v33, v32
	s_nop 1
	s_and_saveexec_b64 s[44:45], vcc
	s_cbranch_execz .LBB0_655
	v_lshl_add_u64 v[34:35], v[48:49], 2, s[26:27]
	s_waitcnt lgkmcnt(0)
	v_add_f32_e32 v32, v32, v33
	global_atomic_add_f32 v[34:35], v32, off
.LBB0_655:
	s_or_b64 exec, exec, s[44:45]
	v_add_u32_e32 v32, 0xa0, v142
	s_waitcnt lgkmcnt(0)
	v_ashrrev_i32_e32 v33, 31, v32
	v_lshlrev_b64 v[34:35], 11, v[32:33]
	v_lshl_add_u64 v[34:35], s[38:39], 0, v[34:35]
	v_lshl_add_u64 v[34:35], s[42:43], 1, v[34:35]
	v_lshl_add_u64 v[34:35], v[34:35], 0, v[80:81]
	v_lshl_add_u64 v[42:43], v[34:35], 0, v[114:115]
	s_waitcnt vmcnt(14)
	v_lshlrev_b32_e32 v44, 16, v228
	v_and_b32_e32 v45, 0xffff0000, v228
	v_pk_fma_f32 v[28:29], v[28:29], 0.5, v[44:45] op_sel_hi:[1,0,1]
	v_lshlrev_b32_e32 v34, 16, v229
	v_and_b32_e32 v35, 0xffff0000, v229
	v_lshlrev_b32_e32 v46, 16, v230
	v_and_b32_e32 v47, 0xffff0000, v230
	v_lshlrev_b32_e32 v36, 16, v231
	v_and_b32_e32 v37, 0xffff0000, v231
	v_mul_f32_e32 v44, v29, v29
	v_pk_fma_f32 v[30:31], v[30:31], 0.5, v[34:35] op_sel_hi:[1,0,1]
	v_pk_fma_f32 v[34:35], v[26:27], 0.5, v[36:37] op_sel_hi:[1,0,1]
	v_pk_fma_f32 v[36:37], v[24:25], 0.5, v[46:47] op_sel_hi:[1,0,1]
	v_cvt_pk_bf16_f32 v24, v28, v29
	v_cvt_pk_bf16_f32 v25, v30, v31
	v_fmac_f32_e32 v44, v28, v28
	v_cvt_pk_bf16_f32 v26, v36, v37
	v_cvt_pk_bf16_f32 v27, v34, v35
	global_store_dwordx4 v[42:43], v[24:27], off
	v_fmac_f32_e32 v44, v30, v30
	v_lshlrev_b32_e32 v28, 16, v234
	v_lshlrev_b32_e32 v24, 16, v232
	v_and_b32_e32 v25, 0xffff0000, v232
	v_lshlrev_b32_e32 v26, 16, v233
	v_and_b32_e32 v27, 0xffff0000, v233
	v_and_b32_e32 v29, 0xffff0000, v234
	v_fmac_f32_e32 v44, v31, v31
	v_lshlrev_b32_e32 v30, 16, v235
	v_and_b32_e32 v31, 0xffff0000, v235
	v_pk_fma_f32 v[22:23], v[22:23], 0.5, v[26:27] op_sel_hi:[1,0,1]
	v_pk_fma_f32 v[20:21], v[20:21], 0.5, v[24:25] op_sel_hi:[1,0,1]
	v_pk_fma_f32 v[26:27], v[16:17], 0.5, v[28:29] op_sel_hi:[1,0,1]
	v_cvt_pk_bf16_f32 v16, v20, v21
	v_pk_fma_f32 v[24:25], v[18:19], 0.5, v[30:31] op_sel_hi:[1,0,1]
	v_cvt_pk_bf16_f32 v17, v22, v23
	v_cvt_pk_bf16_f32 v18, v26, v27
	v_fmac_f32_e32 v44, v36, v36
	v_cvt_pk_bf16_f32 v19, v24, v25
	global_store_dwordx4 v[42:43], v[16:19], off offset:256
	v_fmac_f32_e32 v44, v37, v37
	v_fmac_f32_e32 v44, v34, v34
	v_mul_f32_e32 v16, v21, v21
	v_fmac_f32_e32 v16, v20, v20
	v_fmac_f32_e32 v16, v22, v22
	v_fmac_f32_e32 v16, v23, v23
	v_fmac_f32_e32 v16, v26, v26
	v_fmac_f32_e32 v16, v27, v27
	v_fmac_f32_e32 v16, v24, v24
	v_fmac_f32_e32 v44, v35, v35
	v_fmac_f32_e32 v16, v25, v25
	v_add_f32_e32 v16, v44, v16
	v_mov_b32_e32 v17, v16
	s_nop 1
	v_permlane32_swap_b32 v17, v16
	s_nop 1
	s_waitcnt lgkmcnt(0)
	v_add_f32_e32 v16, v16, v17
	v_mov_b32_e32 v17, v16
	s_nop 1
	v_permlane16_swap_b32 v17, v16
	s_nop 1
	s_and_saveexec_b64 s[44:45], vcc
	s_cbranch_execz .LBB0_657
	v_lshl_add_u64 v[18:19], v[32:33], 2, s[26:27]
	s_waitcnt lgkmcnt(0)
	v_add_f32_e32 v16, v16, v17
	global_atomic_add_f32 v[18:19], v16, off

.LBB0_878:
	s_andn2_b64 vcc, exec, s[0:1]
	s_cbranch_vccnz .LBB0_896
	v_mov_b32_e32 v80, v192
	s_ashr_i32 s7, s6, 31
	v_ashrrev_i32_e32 v83, 2, v80
	v_and_b32_e32 v82, 15, v80
	v_and_b32_e32 v83, 0xffffffc0, v83
	v_add3_u32 v132, v82, s30, v83
	v_ashrrev_i32_e32 v133, 31, v132
	v_lshl_add_u64 v[82:83], v[132:133], 2, s[90:91]
	v_add_co_u32_e32 v82, vcc, s31, v82
	v_bfe_u32 v134, v80, 4, 2
	s_nop 0
	v_addc_co_u32_e32 v83, vcc, 0, v83, vcc
	global_load_dword v135, v[82:83], off
	v_lshrrev_b32_e32 v80, 1, v80
	v_lshlrev_b64 v[82:83], 11, v[132:133]
	v_and_b32_e32 v80, 0x60, v80
	v_lshl_add_u64 v[82:83], s[38:39], 0, v[82:83]
	v_lshl_add_u64 v[136:137], s[6:7], 1, v[82:83]
	v_lshlrev_b32_e32 v82, 1, v80
	v_mov_b32_e32 v83, v81
	v_lshl_add_u64 v[136:137], v[136:137], 0, v[82:83]
	v_lshlrev_b32_e32 v80, 4, v134
	v_lshl_add_u64 v[146:147], v[136:137], 0, v[80:81]
	global_load_dwordx4 v[138:141], v[146:147], off
	global_load_dwordx4 v[142:145], v[146:147], off offset:256
	v_xor_b32_e32 v80, 16, v195
	v_cmp_lt_i32_e32 vcc, v196, v197
	v_cmp_eq_u32_e64 s[40:41], 0, v134
	s_waitcnt vmcnt(0)
	v_lshlrev_b32_e32 v148, 16, v138
	v_cndmask_b32_e32 v137, v195, v196, vcc
	v_cmp_lt_i32_e32 vcc, v80, v197
	v_and_b32_e32 v149, 0xffff0000, v138
	v_lshlrev_b32_e32 v150, 16, v140
	v_cndmask_b32_e32 v80, v195, v80, vcc
	v_lshlrev_b32_e32 v136, 2, v80
	v_fmamk_f32 v80, v135, 0x3b000000, v194
	v_mul_f32_e32 v135, 0x4b800000, v80
	v_cmp_gt_f32_e32 vcc, s19, v80
	v_and_b32_e32 v151, 0xffff0000, v140
	v_lshlrev_b32_e32 v140, 16, v141
	v_cndmask_b32_e32 v80, v80, v135, vcc
	v_rsq_f32_e32 v80, v80
	v_and_b32_e32 v141, 0xffff0000, v141
	v_lshlrev_b32_e32 v160, 16, v142
	v_and_b32_e32 v161, 0xffff0000, v142
	v_mul_f32_e32 v135, 0x45800000, v80
	v_cndmask_b32_e32 v80, v80, v135, vcc
	v_lshlrev_b32_e32 v138, 16, v139
	v_and_b32_e32 v139, 0xffff0000, v139
	v_lshlrev_b32_e32 v142, 16, v143
	v_and_b32_e32 v143, 0xffff0000, v143
	v_lshlrev_b32_e32 v162, 16, v144
	v_and_b32_e32 v163, 0xffff0000, v144
	v_lshlrev_b32_e32 v144, 16, v145
	v_and_b32_e32 v145, 0xffff0000, v145
	v_pk_fma_f32 v[148:149], v[128:129], v[80:81], v[148:149] op_sel_hi:[1,0,1]
	v_pk_fma_f32 v[166:167], v[126:127], v[80:81], v[140:141] op_sel_hi:[1,0,1]
	v_pk_fma_f32 v[140:141], v[124:125], v[80:81], v[150:151] op_sel_hi:[1,0,1]
	v_pk_fma_f32 v[150:151], v[80:81], v[120:121], v[160:161] op_sel_hi:[0,1,1]
	v_pk_fma_f32 v[164:165], v[130:131], v[80:81], v[138:139] op_sel_hi:[1,0,1]
	v_pk_fma_f32 v[142:143], v[80:81], v[122:123], v[142:143] op_sel_hi:[0,1,1]
	v_pk_fma_f32 v[144:145], v[80:81], v[118:119], v[144:145] op_sel_hi:[0,1,1]
	v_pk_fma_f32 v[160:161], v[80:81], v[116:117], v[162:163] op_sel_hi:[0,1,1]
	v_mul_f32_e32 v80, v149, v149
	v_mul_f32_e32 v135, v151, v151
	v_fmac_f32_e32 v80, v148, v148
	v_fmac_f32_e32 v135, v150, v150
	v_fmac_f32_e32 v80, v164, v164
	v_fmac_f32_e32 v135, v142, v142
	v_fmac_f32_e32 v80, v165, v165
	v_fmac_f32_e32 v135, v143, v143
	v_fmac_f32_e32 v80, v140, v140
	v_fmac_f32_e32 v135, v160, v160
	v_fmac_f32_e32 v80, v141, v141
	v_fmac_f32_e32 v135, v161, v161
	v_fmac_f32_e32 v80, v166, v166
	v_fmac_f32_e32 v135, v144, v144
	v_fmac_f32_e32 v80, v167, v167
	v_fmac_f32_e32 v135, v145, v145
	v_add_f32_e32 v80, v80, v135
	v_mov_b32_e32 v135, v80
	s_nop 1
	v_permlane32_swap_b32 v135, v80
	s_nop 1
	v_lshlrev_b32_e32 v137, 2, v137
	v_cvt_pk_bf16_f32 v138, v148, v149
	v_cvt_pk_bf16_f32 v139, v164, v165
	v_cvt_pk_bf16_f32 v140, v140, v141
	s_waitcnt lgkmcnt(0)
	v_add_f32_e32 v80, v80, v135
	v_mov_b32_e32 v135, v80
	s_nop 1
	v_permlane16_swap_b32 v135, v80
	s_nop 1
	v_cvt_pk_bf16_f32 v141, v166, v167
	global_store_dwordx4 v[146:147], v[138:141], off
	s_nop 1
	v_cvt_pk_bf16_f32 v138, v150, v151
	v_cvt_pk_bf16_f32 v139, v142, v143
	v_cvt_pk_bf16_f32 v140, v160, v161
	v_cvt_pk_bf16_f32 v141, v144, v145
	global_store_dwordx4 v[146:147], v[138:141], off offset:256
	s_and_saveexec_b64 s[0:1], s[40:41]
	s_cbranch_execz .LBB0_881
	v_readlane_b32 s10, v253, 47
	v_readlane_b32 s11, v253, 48
	s_waitcnt lgkmcnt(0)
	v_add_f32_e32 v80, v80, v135
	v_lshl_add_u64 v[138:139], v[132:133], 2, s[10:11]
	global_atomic_add_f32 v[138:139], v80, off
.LBB0_881:
	s_or_b64 exec, exec, s[0:1]
	v_lshlrev_b32_e32 v80, 3, v134
	v_add_u32_e32 v134, 16, v132
	s_waitcnt lgkmcnt(0)
	v_ashrrev_i32_e32 v135, 31, v134
	v_lshl_add_u64 v[138:139], v[134:135], 2, s[90:91]
	v_add_co_u32_e32 v138, vcc, 0xe0000, v138
	v_lshlrev_b32_e32 v80, 1, v80
	s_nop 0
	v_addc_co_u32_e32 v139, vcc, 0, v139, vcc
	global_load_dword v133, v[138:139], off
	s_waitcnt vmcnt(0)
	v_fmamk_f32 v133, v133, 0x3b000000, v194
	v_cmp_gt_f32_e32 vcc, s19, v133
	v_mul_f32_e32 v138, 0x4b800000, v133
	s_nop 0
	v_cndmask_b32_e32 v133, v133, v138, vcc
	v_lshlrev_b64 v[138:139], 11, v[134:135]
	v_lshl_add_u64 v[138:139], s[38:39], 0, v[138:139]
	v_lshl_add_u64 v[138:139], s[6:7], 1, v[138:139]
	v_lshl_add_u64 v[138:139], v[138:139], 0, v[82:83]
	v_lshl_add_u64 v[146:147], v[138:139], 0, v[80:81]
	global_load_dwordx4 v[138:141], v[146:147], off
	global_load_dwordx4 v[142:145], v[146:147], off offset:256
	v_rsq_f32_e32 v133, v133
	s_waitcnt vmcnt(1)
	v_lshlrev_b32_e32 v150, 16, v138
	v_mul_f32_e32 v148, 0x45800000, v133
	v_cndmask_b32_e32 v148, v133, v148, vcc
	v_and_b32_e32 v151, 0xffff0000, v138
	v_pk_fma_f32 v[150:151], v[112:113], v[148:149], v[150:151] op_sel_hi:[1,0,1]
	v_lshlrev_b32_e32 v138, 16, v139
	v_and_b32_e32 v139, 0xffff0000, v139
	v_mul_f32_e32 v83, v151, v151
	v_pk_fma_f32 v[162:163], v[114:115], v[148:149], v[138:139] op_sel_hi:[1,0,1]
	v_fmac_f32_e32 v83, v150, v150
	v_lshlrev_b32_e32 v160, 16, v140
	v_and_b32_e32 v161, 0xffff0000, v140
	v_fmac_f32_e32 v83, v162, v162
	v_lshlrev_b32_e32 v140, 16, v141
	v_and_b32_e32 v141, 0xffff0000, v141
	v_pk_fma_f32 v[160:161], v[108:109], v[148:149], v[160:161] op_sel_hi:[1,0,1]
	v_cvt_pk_bf16_f32 v138, v150, v151
	v_cvt_pk_bf16_f32 v139, v162, v163
	v_fmac_f32_e32 v83, v163, v163
	v_pk_fma_f32 v[164:165], v[110:111], v[148:149], v[140:141] op_sel_hi:[1,0,1]
	v_cvt_pk_bf16_f32 v140, v160, v161
	v_fmac_f32_e32 v83, v160, v160
	v_cvt_pk_bf16_f32 v141, v164, v165
	global_store_dwordx4 v[146:147], v[138:141], off
	v_fmac_f32_e32 v83, v161, v161
	v_fmac_f32_e32 v83, v164, v164
	s_waitcnt vmcnt(1)
	v_lshlrev_b32_e32 v138, 16, v142
	v_and_b32_e32 v139, 0xffff0000, v142
	v_pk_fma_f32 v[160:161], v[148:149], v[104:105], v[138:139] op_sel_hi:[0,1,1]
	v_lshlrev_b32_e32 v140, 16, v143
	v_and_b32_e32 v141, 0xffff0000, v143
	v_mul_f32_e32 v133, v161, v161
	v_pk_fma_f32 v[150:151], v[148:149], v[106:107], v[140:141] op_sel_hi:[0,1,1]
	v_fmac_f32_e32 v133, v160, v160
	v_lshlrev_b32_e32 v142, 16, v144
	v_and_b32_e32 v143, 0xffff0000, v144
	v_fmac_f32_e32 v133, v150, v150
	v_pk_fma_f32 v[142:143], v[148:149], v[100:101], v[142:143] op_sel_hi:[0,1,1]
	v_fmac_f32_e32 v133, v151, v151
	v_lshlrev_b32_e32 v144, 16, v145
	v_and_b32_e32 v145, 0xffff0000, v145
	v_fmac_f32_e32 v133, v142, v142
	v_pk_fma_f32 v[144:145], v[148:149], v[102:103], v[144:145] op_sel_hi:[0,1,1]
	v_fmac_f32_e32 v133, v143, v143
	v_fmac_f32_e32 v133, v144, v144
	v_fmac_f32_e32 v83, v165, v165
	v_fmac_f32_e32 v133, v145, v145
	v_add_f32_e32 v83, v83, v133
	v_mov_b32_e32 v133, v83
	s_nop 1
	v_permlane32_swap_b32 v133, v83
	s_nop 1
	v_cvt_pk_bf16_f32 v138, v160, v161
	v_cvt_pk_bf16_f32 v139, v150, v151
	v_cvt_pk_bf16_f32 v140, v142, v143
	v_cvt_pk_bf16_f32 v141, v144, v145
	s_waitcnt lgkmcnt(0)
	v_add_f32_e32 v83, v83, v133
	v_mov_b32_e32 v133, v83
	s_nop 1
	v_permlane16_swap_b32 v133, v83
	s_nop 1
	global_store_dwordx4 v[146:147], v[138:141], off offset:256
	s_and_saveexec_b64 s[0:1], s[40:41]
	s_cbranch_execz .LBB0_883
	v_readlane_b32 s10, v253, 47
	v_readlane_b32 s11, v253, 48
	s_waitcnt lgkmcnt(0)
	v_add_f32_e32 v83, v83, v133
	v_lshl_add_u64 v[134:135], v[134:135], 2, s[10:11]
	global_atomic_add_f32 v[134:135], v83, off
.LBB0_883:
	s_or_b64 exec, exec, s[0:1]
	v_add_u32_e32 v134, 32, v132
	v_ashrrev_i32_e32 v135, 31, v134
	v_lshl_add_u64 v[138:139], v[134:135], 2, s[90:91]
	v_add_co_u32_e32 v138, vcc, 0xe0000, v138
	s_nop 1
	v_addc_co_u32_e32 v139, vcc, 0, v139, vcc
	global_load_dword v83, v[138:139], off
	v_lshlrev_b64 v[138:139], 11, v[134:135]
	v_lshl_add_u64 v[138:139], s[38:39], 0, v[138:139]
	v_lshl_add_u64 v[138:139], s[6:7], 1, v[138:139]
	s_waitcnt vmcnt(0)
	v_fmamk_f32 v83, v83, 0x3b000000, v194
	v_cmp_gt_f32_e32 vcc, s19, v83
	s_waitcnt lgkmcnt(0)
	v_mul_f32_e32 v133, 0x4b800000, v83
	v_cndmask_b32_e32 v83, v83, v133, vcc
	v_rsq_f32_e32 v133, v83
	v_mov_b32_e32 v83, v81
	v_lshl_add_u64 v[138:139], v[138:139], 0, v[82:83]
	v_lshl_add_u64 v[146:147], v[138:139], 0, v[80:81]
	global_load_dwordx4 v[138:141], v[146:147], off
	global_load_dwordx4 v[142:145], v[146:147], off offset:256
	v_mul_f32_e32 v148, 0x45800000, v133
	v_cndmask_b32_e32 v148, v133, v148, vcc
	s_waitcnt vmcnt(1)
	v_lshlrev_b32_e32 v150, 16, v138
	v_and_b32_e32 v151, 0xffff0000, v138
	v_pk_fma_f32 v[150:151], v[96:97], v[148:149], v[150:151] op_sel_hi:[1,0,1]
	v_lshlrev_b32_e32 v138, 16, v139
	v_and_b32_e32 v139, 0xffff0000, v139
	v_mul_f32_e32 v133, v151, v151
	v_pk_fma_f32 v[162:163], v[98:99], v[148:149], v[138:139] op_sel_hi:[1,0,1]
	v_fmac_f32_e32 v133, v150, v150
	v_lshlrev_b32_e32 v160, 16, v140
	v_and_b32_e32 v161, 0xffff0000, v140
	v_fmac_f32_e32 v133, v162, v162
	v_lshlrev_b32_e32 v140, 16, v141
	v_and_b32_e32 v141, 0xffff0000, v141
	v_pk_fma_f32 v[160:161], v[92:93], v[148:149], v[160:161] op_sel_hi:[1,0,1]
	v_cvt_pk_bf16_f32 v138, v150, v151
	v_cvt_pk_bf16_f32 v139, v162, v163
	v_fmac_f32_e32 v133, v163, v163
	v_pk_fma_f32 v[164:165], v[94:95], v[148:149], v[140:141] op_sel_hi:[1,0,1]
	v_cvt_pk_bf16_f32 v140, v160, v161
	v_fmac_f32_e32 v133, v160, v160
	v_cvt_pk_bf16_f32 v141, v164, v165
	global_store_dwordx4 v[146:147], v[138:141], off
	v_fmac_f32_e32 v133, v161, v161
	v_fmac_f32_e32 v133, v164, v164
	s_waitcnt vmcnt(1)
	v_lshlrev_b32_e32 v138, 16, v142
	v_and_b32_e32 v139, 0xffff0000, v142
	v_lshlrev_b32_e32 v140, 16, v143
	v_and_b32_e32 v141, 0xffff0000, v143
	v_lshlrev_b32_e32 v142, 16, v144
	v_and_b32_e32 v143, 0xffff0000, v144
	v_lshlrev_b32_e32 v144, 16, v145
	v_and_b32_e32 v145, 0xffff0000, v145
	v_pk_fma_f32 v[160:161], v[148:149], v[88:89], v[138:139] op_sel_hi:[0,1,1]
	v_cvt_pk_bf16_f32 v138, v160, v161
	v_pk_fma_f32 v[150:151], v[148:149], v[90:91], v[140:141] op_sel_hi:[0,1,1]
	v_pk_fma_f32 v[144:145], v[148:149], v[86:87], v[144:145] op_sel_hi:[0,1,1]
	v_pk_fma_f32 v[142:143], v[148:149], v[84:85], v[142:143] op_sel_hi:[0,1,1]
	v_cvt_pk_bf16_f32 v139, v150, v151
	v_cvt_pk_bf16_f32 v140, v142, v143
	v_cvt_pk_bf16_f32 v141, v144, v145
	global_store_dwordx4 v[146:147], v[138:141], off offset:256
	v_fmac_f32_e32 v133, v165, v165
	s_nop 0
	v_mul_f32_e32 v138, v161, v161
	v_fmac_f32_e32 v138, v160, v160
	v_fmac_f32_e32 v138, v150, v150
	v_fmac_f32_e32 v138, v151, v151
	v_fmac_f32_e32 v138, v142, v142
	v_fmac_f32_e32 v138, v143, v143
	v_fmac_f32_e32 v138, v144, v144
	v_fmac_f32_e32 v138, v145, v145
	v_add_f32_e32 v133, v133, v138
	v_mov_b32_e32 v138, v133
	s_nop 1
	v_permlane32_swap_b32 v138, v133
	s_nop 1
	s_waitcnt lgkmcnt(0)
	v_add_f32_e32 v133, v133, v138
	v_mov_b32_e32 v138, v133
	s_nop 1
	v_permlane16_swap_b32 v138, v133
	s_nop 1
	s_and_saveexec_b64 s[0:1], s[40:41]
	s_cbranch_execz .LBB0_885
	v_readlane_b32 s10, v253, 47
	v_readlane_b32 s11, v253, 48
	s_waitcnt lgkmcnt(0)
	v_add_f32_e32 v133, v133, v138
	v_lshl_add_u64 v[134:135], v[134:135], 2, s[10:11]
	global_atomic_add_f32 v[134:135], v133, off
.LBB0_885:
	s_or_b64 exec, exec, s[0:1]
	v_add_u32_e32 v134, 48, v132
	v_ashrrev_i32_e32 v135, 31, v134
	s_waitcnt lgkmcnt(0)
	v_lshl_add_u64 v[138:139], v[134:135], 2, s[90:91]
	v_add_co_u32_e32 v138, vcc, 0xe0000, v138
	s_nop 1
	v_addc_co_u32_e32 v139, vcc, 0, v139, vcc
	global_load_dword v133, v[138:139], off
	s_waitcnt vmcnt(0)
	v_fmamk_f32 v133, v133, 0x3b000000, v194
	v_cmp_gt_f32_e32 vcc, s19, v133
	v_mul_f32_e32 v138, 0x4b800000, v133
	s_nop 0
	v_cndmask_b32_e32 v133, v133, v138, vcc
	v_lshlrev_b64 v[138:139], 11, v[134:135]
	v_lshl_add_u64 v[138:139], s[38:39], 0, v[138:139]
	v_lshl_add_u64 v[138:139], s[6:7], 1, v[138:139]
	v_lshl_add_u64 v[138:139], v[138:139], 0, v[82:83]
	v_lshl_add_u64 v[146:147], v[138:139], 0, v[80:81]
	global_load_dwordx4 v[138:141], v[146:147], off
	global_load_dwordx4 v[142:145], v[146:147], off offset:256
	v_rsq_f32_e32 v133, v133
	s_waitcnt vmcnt(1)
	v_lshlrev_b32_e32 v150, 16, v138
	v_mul_f32_e32 v148, 0x45800000, v133
	v_cndmask_b32_e32 v148, v133, v148, vcc
	v_and_b32_e32 v151, 0xffff0000, v138
	v_pk_fma_f32 v[150:151], v[76:77], v[148:149], v[150:151] op_sel_hi:[1,0,1]
	v_lshlrev_b32_e32 v138, 16, v139
	v_and_b32_e32 v139, 0xffff0000, v139
	v_mul_f32_e32 v83, v151, v151
	v_pk_fma_f32 v[162:163], v[78:79], v[148:149], v[138:139] op_sel_hi:[1,0,1]
	v_fmac_f32_e32 v83, v150, v150
	v_lshlrev_b32_e32 v160, 16, v140
	v_and_b32_e32 v161, 0xffff0000, v140
	v_fmac_f32_e32 v83, v162, v162
	v_lshlrev_b32_e32 v140, 16, v141
	v_and_b32_e32 v141, 0xffff0000, v141
	v_pk_fma_f32 v[160:161], v[72:73], v[148:149], v[160:161] op_sel_hi:[1,0,1]
	v_cvt_pk_bf16_f32 v138, v150, v151
	v_cvt_pk_bf16_f32 v139, v162, v163
	v_fmac_f32_e32 v83, v163, v163
	v_pk_fma_f32 v[164:165], v[74:75], v[148:149], v[140:141] op_sel_hi:[1,0,1]
	v_cvt_pk_bf16_f32 v140, v160, v161
	v_fmac_f32_e32 v83, v160, v160
	v_cvt_pk_bf16_f32 v141, v164, v165
	global_store_dwordx4 v[146:147], v[138:141], off
	v_fmac_f32_e32 v83, v161, v161
	v_fmac_f32_e32 v83, v164, v164
	s_waitcnt vmcnt(1)
	v_lshlrev_b32_e32 v138, 16, v142
	v_and_b32_e32 v139, 0xffff0000, v142
	v_pk_fma_f32 v[160:161], v[148:149], v[68:69], v[138:139] op_sel_hi:[0,1,1]
	v_lshlrev_b32_e32 v140, 16, v143
	v_and_b32_e32 v141, 0xffff0000, v143
	v_mul_f32_e32 v133, v161, v161
	v_pk_fma_f32 v[150:151], v[148:149], v[70:71], v[140:141] op_sel_hi:[0,1,1]
	v_fmac_f32_e32 v133, v160, v160
	v_lshlrev_b32_e32 v142, 16, v144
	v_and_b32_e32 v143, 0xffff0000, v144
	v_fmac_f32_e32 v133, v150, v150
	v_pk_fma_f32 v[142:143], v[148:149], v[64:65], v[142:143] op_sel_hi:[0,1,1]
	v_fmac_f32_e32 v133, v151, v151
	v_lshlrev_b32_e32 v144, 16, v145
	v_and_b32_e32 v145, 0xffff0000, v145
	v_fmac_f32_e32 v133, v142, v142
	v_pk_fma_f32 v[144:145], v[148:149], v[66:67], v[144:145] op_sel_hi:[0,1,1]
	v_fmac_f32_e32 v133, v143, v143
	v_fmac_f32_e32 v133, v144, v144
	v_fmac_f32_e32 v83, v165, v165
	v_fmac_f32_e32 v133, v145, v145
	v_add_f32_e32 v83, v83, v133
	v_mov_b32_e32 v133, v83
	s_nop 1
	v_permlane32_swap_b32 v133, v83
	s_nop 1
	v_cvt_pk_bf16_f32 v138, v160, v161
	v_cvt_pk_bf16_f32 v139, v150, v151
	v_cvt_pk_bf16_f32 v140, v142, v143
	v_cvt_pk_bf16_f32 v141, v144, v145
	s_waitcnt lgkmcnt(0)
	v_add_f32_e32 v83, v83, v133
	v_mov_b32_e32 v133, v83
	s_nop 1
	v_permlane16_swap_b32 v133, v83
	s_nop 1
	global_store_dwordx4 v[146:147], v[138:141], off offset:256
	s_and_saveexec_b64 s[0:1], s[40:41]
	s_cbranch_execz .LBB0_887
	v_readlane_b32 s10, v253, 47
	v_readlane_b32 s11, v253, 48
	s_waitcnt lgkmcnt(0)
	v_add_f32_e32 v83, v83, v133
	v_lshl_add_u64 v[134:135], v[134:135], 2, s[10:11]
	global_atomic_add_f32 v[134:135], v83, off
.LBB0_887:
	s_or_b64 exec, exec, s[0:1]
	v_add_u32_e32 v134, 0x80, v132
	v_ashrrev_i32_e32 v135, 31, v134
	v_lshl_add_u64 v[138:139], v[134:135], 2, s[90:91]
	v_add_co_u32_e32 v138, vcc, 0xe0000, v138
	s_nop 1
	v_addc_co_u32_e32 v139, vcc, 0, v139, vcc
	global_load_dword v83, v[138:139], off
	v_lshlrev_b64 v[138:139], 11, v[134:135]
	v_lshl_add_u64 v[138:139], s[38:39], 0, v[138:139]
	v_lshl_add_u64 v[138:139], s[6:7], 1, v[138:139]
	s_waitcnt vmcnt(0)
	v_fmamk_f32 v83, v83, 0x3b000000, v194
	v_cmp_gt_f32_e32 vcc, s19, v83
	s_waitcnt lgkmcnt(0)
	v_mul_f32_e32 v133, 0x4b800000, v83
	v_cndmask_b32_e32 v83, v83, v133, vcc
	v_rsq_f32_e32 v133, v83
	v_mov_b32_e32 v83, v81
	v_lshl_add_u64 v[138:139], v[138:139], 0, v[82:83]
	v_lshl_add_u64 v[146:147], v[138:139], 0, v[80:81]
	global_load_dwordx4 v[138:141], v[146:147], off
	global_load_dwordx4 v[142:145], v[146:147], off offset:256
	v_mul_f32_e32 v148, 0x45800000, v133
	v_cndmask_b32_e32 v148, v133, v148, vcc
	s_waitcnt vmcnt(1)
	v_lshlrev_b32_e32 v150, 16, v138
	v_and_b32_e32 v151, 0xffff0000, v138
	v_pk_fma_f32 v[150:151], v[60:61], v[148:149], v[150:151] op_sel_hi:[1,0,1]
	v_lshlrev_b32_e32 v138, 16, v139
	v_and_b32_e32 v139, 0xffff0000, v139
	v_mul_f32_e32 v133, v151, v151
	v_pk_fma_f32 v[162:163], v[62:63], v[148:149], v[138:139] op_sel_hi:[1,0,1]
	v_fmac_f32_e32 v133, v150, v150
	v_lshlrev_b32_e32 v160, 16, v140
	v_and_b32_e32 v161, 0xffff0000, v140
	v_fmac_f32_e32 v133, v162, v162
	v_lshlrev_b32_e32 v140, 16, v141
	v_and_b32_e32 v141, 0xffff0000, v141
	v_pk_fma_f32 v[160:161], v[56:57], v[148:149], v[160:161] op_sel_hi:[1,0,1]
	v_cvt_pk_bf16_f32 v138, v150, v151
	v_cvt_pk_bf16_f32 v139, v162, v163
	v_fmac_f32_e32 v133, v163, v163
	v_pk_fma_f32 v[164:165], v[58:59], v[148:149], v[140:141] op_sel_hi:[1,0,1]
	v_cvt_pk_bf16_f32 v140, v160, v161
	v_fmac_f32_e32 v133, v160, v160
	v_cvt_pk_bf16_f32 v141, v164, v165
	global_store_dwordx4 v[146:147], v[138:141], off
	v_fmac_f32_e32 v133, v161, v161
	v_fmac_f32_e32 v133, v164, v164
	s_waitcnt vmcnt(1)
	v_lshlrev_b32_e32 v138, 16, v142
	v_and_b32_e32 v139, 0xffff0000, v142
	v_lshlrev_b32_e32 v140, 16, v143
	v_and_b32_e32 v141, 0xffff0000, v143
	v_lshlrev_b32_e32 v142, 16, v144
	v_and_b32_e32 v143, 0xffff0000, v144
	v_lshlrev_b32_e32 v144, 16, v145
	v_and_b32_e32 v145, 0xffff0000, v145
	v_pk_fma_f32 v[160:161], v[148:149], v[52:53], v[138:139] op_sel_hi:[0,1,1]
	v_cvt_pk_bf16_f32 v138, v160, v161
	v_pk_fma_f32 v[150:151], v[148:149], v[54:55], v[140:141] op_sel_hi:[0,1,1]
	v_pk_fma_f32 v[144:145], v[148:149], v[50:51], v[144:145] op_sel_hi:[0,1,1]
	v_pk_fma_f32 v[142:143], v[148:149], v[48:49], v[142:143] op_sel_hi:[0,1,1]
	v_cvt_pk_bf16_f32 v139, v150, v151
	v_cvt_pk_bf16_f32 v140, v142, v143
	v_cvt_pk_bf16_f32 v141, v144, v145
	global_store_dwordx4 v[146:147], v[138:141], off offset:256
	v_fmac_f32_e32 v133, v165, v165
	s_nop 0
	v_mul_f32_e32 v138, v161, v161
	v_fmac_f32_e32 v138, v160, v160
	v_fmac_f32_e32 v138, v150, v150
	v_fmac_f32_e32 v138, v151, v151
	v_fmac_f32_e32 v138, v142, v142
	v_fmac_f32_e32 v138, v143, v143
	v_fmac_f32_e32 v138, v144, v144
	v_fmac_f32_e32 v138, v145, v145
	v_add_f32_e32 v133, v133, v138
	v_mov_b32_e32 v138, v133
	s_nop 1
	v_permlane32_swap_b32 v138, v133
	s_nop 1
	s_waitcnt lgkmcnt(0)
	v_add_f32_e32 v133, v133, v138
	v_mov_b32_e32 v138, v133
	s_nop 1
	v_permlane16_swap_b32 v138, v133
	s_nop 1
	s_and_saveexec_b64 s[0:1], s[40:41]
	s_cbranch_execz .LBB0_889
	v_readlane_b32 s10, v253, 47
	v_readlane_b32 s11, v253, 48
	s_waitcnt lgkmcnt(0)
	v_add_f32_e32 v133, v133, v138
	v_lshl_add_u64 v[134:135], v[134:135], 2, s[10:11]
	global_atomic_add_f32 v[134:135], v133, off
.LBB0_889:
	s_or_b64 exec, exec, s[0:1]
	v_add_u32_e32 v134, 0x90, v132
	v_ashrrev_i32_e32 v135, 31, v134
	s_waitcnt lgkmcnt(0)
	v_lshl_add_u64 v[138:139], v[134:135], 2, s[90:91]
	v_add_co_u32_e32 v138, vcc, 0xe0000, v138
	s_nop 1
	v_addc_co_u32_e32 v139, vcc, 0, v139, vcc
	global_load_dword v133, v[138:139], off
	s_waitcnt vmcnt(0)
	v_fmamk_f32 v133, v133, 0x3b000000, v194
	v_cmp_gt_f32_e32 vcc, s19, v133
	v_mul_f32_e32 v138, 0x4b800000, v133
	s_nop 0
	v_cndmask_b32_e32 v133, v133, v138, vcc
	v_lshlrev_b64 v[138:139], 11, v[134:135]
	v_lshl_add_u64 v[138:139], s[38:39], 0, v[138:139]
	v_lshl_add_u64 v[138:139], s[6:7], 1, v[138:139]
	v_lshl_add_u64 v[138:139], v[138:139], 0, v[82:83]
	v_lshl_add_u64 v[146:147], v[138:139], 0, v[80:81]
	global_load_dwordx4 v[138:141], v[146:147], off
	global_load_dwordx4 v[142:145], v[146:147], off offset:256
	v_rsq_f32_e32 v133, v133
	s_waitcnt vmcnt(1)
	v_lshlrev_b32_e32 v150, 16, v138
	v_mul_f32_e32 v148, 0x45800000, v133
	v_cndmask_b32_e32 v148, v133, v148, vcc
	v_and_b32_e32 v151, 0xffff0000, v138
	v_pk_fma_f32 v[150:151], v[44:45], v[148:149], v[150:151] op_sel_hi:[1,0,1]
	v_lshlrev_b32_e32 v138, 16, v139
	v_and_b32_e32 v139, 0xffff0000, v139
	v_mul_f32_e32 v83, v151, v151
	v_pk_fma_f32 v[162:163], v[46:47], v[148:149], v[138:139] op_sel_hi:[1,0,1]
	v_fmac_f32_e32 v83, v150, v150
	v_lshlrev_b32_e32 v160, 16, v140
	v_and_b32_e32 v161, 0xffff0000, v140
	v_fmac_f32_e32 v83, v162, v162
	v_lshlrev_b32_e32 v140, 16, v141
	v_and_b32_e32 v141, 0xffff0000, v141
	v_pk_fma_f32 v[160:161], v[40:41], v[148:149], v[160:161] op_sel_hi:[1,0,1]
	v_cvt_pk_bf16_f32 v138, v150, v151
	v_cvt_pk_bf16_f32 v139, v162, v163
	v_fmac_f32_e32 v83, v163, v163
	v_pk_fma_f32 v[164:165], v[42:43], v[148:149], v[140:141] op_sel_hi:[1,0,1]
	v_cvt_pk_bf16_f32 v140, v160, v161
	v_fmac_f32_e32 v83, v160, v160
	v_cvt_pk_bf16_f32 v141, v164, v165
	global_store_dwordx4 v[146:147], v[138:141], off
	v_fmac_f32_e32 v83, v161, v161
	v_fmac_f32_e32 v83, v164, v164
	s_waitcnt vmcnt(1)
	v_lshlrev_b32_e32 v138, 16, v142
	v_and_b32_e32 v139, 0xffff0000, v142
	v_pk_fma_f32 v[160:161], v[148:149], v[36:37], v[138:139] op_sel_hi:[0,1,1]
	v_lshlrev_b32_e32 v140, 16, v143
	v_and_b32_e32 v141, 0xffff0000, v143
	v_mul_f32_e32 v133, v161, v161
	v_pk_fma_f32 v[150:151], v[148:149], v[38:39], v[140:141] op_sel_hi:[0,1,1]
	v_fmac_f32_e32 v133, v160, v160
	v_lshlrev_b32_e32 v142, 16, v144
	v_and_b32_e32 v143, 0xffff0000, v144
	v_fmac_f32_e32 v133, v150, v150
	v_pk_fma_f32 v[142:143], v[148:149], v[32:33], v[142:143] op_sel_hi:[0,1,1]
	v_fmac_f32_e32 v133, v151, v151
	v_lshlrev_b32_e32 v144, 16, v145
	v_and_b32_e32 v145, 0xffff0000, v145
	v_fmac_f32_e32 v133, v142, v142
	v_pk_fma_f32 v[144:145], v[148:149], v[34:35], v[144:145] op_sel_hi:[0,1,1]
	v_fmac_f32_e32 v133, v143, v143
	v_fmac_f32_e32 v133, v144, v144
	v_fmac_f32_e32 v83, v165, v165
	v_fmac_f32_e32 v133, v145, v145
	v_add_f32_e32 v83, v83, v133
	v_mov_b32_e32 v133, v83
	s_nop 1
	v_permlane32_swap_b32 v133, v83
	s_nop 1
	v_cvt_pk_bf16_f32 v138, v160, v161
	v_cvt_pk_bf16_f32 v139, v150, v151
	v_cvt_pk_bf16_f32 v140, v142, v143
	v_cvt_pk_bf16_f32 v141, v144, v145
	s_waitcnt lgkmcnt(0)
	v_add_f32_e32 v83, v83, v133
	v_mov_b32_e32 v133, v83
	s_nop 1
	v_permlane16_swap_b32 v133, v83
	s_nop 1
	global_store_dwordx4 v[146:147], v[138:141], off offset:256
	s_and_saveexec_b64 s[0:1], s[40:41]
	s_cbranch_execz .LBB0_891
	v_readlane_b32 s10, v253, 47
	v_readlane_b32 s11, v253, 48
	s_waitcnt lgkmcnt(0)
	v_add_f32_e32 v83, v83, v133
	v_lshl_add_u64 v[134:135], v[134:135], 2, s[10:11]
	global_atomic_add_f32 v[134:135], v83, off
.LBB0_891:
	s_or_b64 exec, exec, s[0:1]
	v_add_u32_e32 v134, 0xa0, v132
	v_ashrrev_i32_e32 v135, 31, v134
	v_lshl_add_u64 v[138:139], v[134:135], 2, s[90:91]
	v_add_co_u32_e32 v138, vcc, 0xe0000, v138
	s_nop 1
	v_addc_co_u32_e32 v139, vcc, 0, v139, vcc
	global_load_dword v83, v[138:139], off
	v_lshlrev_b64 v[138:139], 11, v[134:135]
	v_lshl_add_u64 v[138:139], s[38:39], 0, v[138:139]
	v_lshl_add_u64 v[138:139], s[6:7], 1, v[138:139]
	s_waitcnt vmcnt(0)
	v_fmamk_f32 v83, v83, 0x3b000000, v194
	v_cmp_gt_f32_e32 vcc, s19, v83
	s_waitcnt lgkmcnt(0)
	v_mul_f32_e32 v133, 0x4b800000, v83
	v_cndmask_b32_e32 v83, v83, v133, vcc
	v_rsq_f32_e32 v133, v83
	v_mov_b32_e32 v83, v81
	v_lshl_add_u64 v[138:139], v[138:139], 0, v[82:83]
	v_lshl_add_u64 v[146:147], v[138:139], 0, v[80:81]
	global_load_dwordx4 v[138:141], v[146:147], off
	global_load_dwordx4 v[142:145], v[146:147], off offset:256
	v_mul_f32_e32 v148, 0x45800000, v133
	v_cndmask_b32_e32 v148, v133, v148, vcc
	s_waitcnt vmcnt(1)
	v_lshlrev_b32_e32 v150, 16, v138
	v_and_b32_e32 v151, 0xffff0000, v138
	v_pk_fma_f32 v[150:151], v[28:29], v[148:149], v[150:151] op_sel_hi:[1,0,1]
	v_lshlrev_b32_e32 v138, 16, v139
	v_and_b32_e32 v139, 0xffff0000, v139
	v_mul_f32_e32 v133, v151, v151
	v_pk_fma_f32 v[162:163], v[30:31], v[148:149], v[138:139] op_sel_hi:[1,0,1]
	v_fmac_f32_e32 v133, v150, v150
	v_lshlrev_b32_e32 v160, 16, v140
	v_and_b32_e32 v161, 0xffff0000, v140
	v_fmac_f32_e32 v133, v162, v162
	v_lshlrev_b32_e32 v140, 16, v141
	v_and_b32_e32 v141, 0xffff0000, v141
	v_pk_fma_f32 v[160:161], v[24:25], v[148:149], v[160:161] op_sel_hi:[1,0,1]
	v_cvt_pk_bf16_f32 v138, v150, v151
	v_cvt_pk_bf16_f32 v139, v162, v163
	v_fmac_f32_e32 v133, v163, v163
	v_pk_fma_f32 v[164:165], v[26:27], v[148:149], v[140:141] op_sel_hi:[1,0,1]
	v_cvt_pk_bf16_f32 v140, v160, v161
	v_fmac_f32_e32 v133, v160, v160
	v_cvt_pk_bf16_f32 v141, v164, v165
	global_store_dwordx4 v[146:147], v[138:141], off
	v_fmac_f32_e32 v133, v161, v161
	v_fmac_f32_e32 v133, v164, v164
	s_waitcnt vmcnt(1)
	v_lshlrev_b32_e32 v138, 16, v142
	v_and_b32_e32 v139, 0xffff0000, v142
	v_lshlrev_b32_e32 v140, 16, v143
	v_and_b32_e32 v141, 0xffff0000, v143
	v_lshlrev_b32_e32 v142, 16, v144
	v_and_b32_e32 v143, 0xffff0000, v144
	v_lshlrev_b32_e32 v144, 16, v145
	v_and_b32_e32 v145, 0xffff0000, v145
	v_pk_fma_f32 v[160:161], v[148:149], v[20:21], v[138:139] op_sel_hi:[0,1,1]
	v_cvt_pk_bf16_f32 v138, v160, v161
	v_pk_fma_f32 v[150:151], v[148:149], v[22:23], v[140:141] op_sel_hi:[0,1,1]
	v_pk_fma_f32 v[144:145], v[148:149], v[18:19], v[144:145] op_sel_hi:[0,1,1]
	v_pk_fma_f32 v[142:143], v[148:149], v[16:17], v[142:143] op_sel_hi:[0,1,1]
	v_cvt_pk_bf16_f32 v139, v150, v151
	v_cvt_pk_bf16_f32 v140, v142, v143
	v_cvt_pk_bf16_f32 v141, v144, v145
	global_store_dwordx4 v[146:147], v[138:141], off offset:256
	v_fmac_f32_e32 v133, v165, v165
	s_nop 0
	v_mul_f32_e32 v138, v161, v161
	v_fmac_f32_e32 v138, v160, v160
	v_fmac_f32_e32 v138, v150, v150
	v_fmac_f32_e32 v138, v151, v151
	v_fmac_f32_e32 v138, v142, v142
	v_fmac_f32_e32 v138, v143, v143
	v_fmac_f32_e32 v138, v144, v144
	v_fmac_f32_e32 v138, v145, v145
	v_add_f32_e32 v133, v133, v138
	v_mov_b32_e32 v138, v133
	s_nop 1
	v_permlane32_swap_b32 v138, v133
	s_nop 1
	s_waitcnt lgkmcnt(0)
	v_add_f32_e32 v133, v133, v138
	v_mov_b32_e32 v138, v133
	s_nop 1
	v_permlane16_swap_b32 v138, v133
	s_nop 1
	s_and_saveexec_b64 s[0:1], s[40:41]
	s_cbranch_execz .LBB0_893
	v_readlane_b32 s10, v253, 47
	v_readlane_b32 s11, v253, 48
	s_waitcnt lgkmcnt(0)
	v_add_f32_e32 v133, v133, v138
	v_lshl_add_u64 v[134:135], v[134:135], 2, s[10:11]
	global_atomic_add_f32 v[134:135], v133, off
.LBB0_893:
	s_or_b64 exec, exec, s[0:1]
	v_add_u32_e32 v132, 0xb0, v132
	v_ashrrev_i32_e32 v133, 31, v132
	v_lshl_add_u64 v[134:135], v[132:133], 2, s[90:91]
	v_add_co_u32_e32 v134, vcc, 0xe0000, v134
	s_nop 1
	v_addc_co_u32_e32 v135, vcc, 0, v135, vcc
	global_load_dword v134, v[134:135], off
	s_waitcnt vmcnt(0)
	v_fmamk_f32 v134, v134, 0x3b000000, v194
	v_cmp_gt_f32_e32 vcc, s19, v134
	v_mul_f32_e32 v135, 0x4b800000, v134
	s_nop 0
	v_cndmask_b32_e32 v134, v134, v135, vcc
	v_rsq_f32_e32 v146, v134
	v_lshlrev_b64 v[134:135], 11, v[132:133]
	v_lshl_add_u64 v[134:135], s[38:39], 0, v[134:135]
	v_lshl_add_u64 v[134:135], s[6:7], 1, v[134:135]
	v_lshl_add_u64 v[82:83], v[134:135], 0, v[82:83]
	v_lshl_add_u64 v[82:83], v[82:83], 0, v[80:81]
	s_waitcnt lgkmcnt(0)
	global_load_dwordx4 v[138:141], v[82:83], off
	global_load_dwordx4 v[142:145], v[82:83], off offset:256
	v_mul_f32_e32 v147, 0x45800000, v146
	v_cndmask_b32_e32 v80, v146, v147, vcc
	s_waitcnt vmcnt(1)
	v_lshlrev_b32_e32 v134, 16, v138
	v_and_b32_e32 v135, 0xffff0000, v138
	v_pk_fma_f32 v[134:135], v[12:13], v[80:81], v[134:135] op_sel_hi:[1,0,1]
	v_lshlrev_b32_e32 v138, 16, v139
	v_and_b32_e32 v139, 0xffff0000, v139
	v_mul_f32_e32 v160, v135, v135
	v_pk_fma_f32 v[148:149], v[14:15], v[80:81], v[138:139] op_sel_hi:[1,0,1]
	v_fmac_f32_e32 v160, v134, v134
	v_lshlrev_b32_e32 v146, 16, v140
	v_and_b32_e32 v147, 0xffff0000, v140
	v_lshlrev_b32_e32 v140, 16, v141
	v_and_b32_e32 v141, 0xffff0000, v141
	v_fmac_f32_e32 v160, v148, v148
	v_pk_fma_f32 v[150:151], v[10:11], v[80:81], v[140:141] op_sel_hi:[1,0,1]
	v_pk_fma_f32 v[146:147], v[8:9], v[80:81], v[146:147] op_sel_hi:[1,0,1]
	v_cvt_pk_bf16_f32 v138, v134, v135
	v_cvt_pk_bf16_f32 v139, v148, v149
	v_fmac_f32_e32 v160, v149, v149
	v_cvt_pk_bf16_f32 v140, v146, v147
	v_cvt_pk_bf16_f32 v141, v150, v151
	s_waitcnt vmcnt(0)
	v_lshlrev_b32_e32 v134, 16, v142
	v_and_b32_e32 v135, 0xffff0000, v142
	global_store_dwordx4 v[82:83], v[138:141], off
	v_fmac_f32_e32 v160, v146, v146
	v_lshlrev_b32_e32 v142, 16, v145
	v_lshlrev_b32_e32 v138, 16, v143
	v_and_b32_e32 v139, 0xffff0000, v143
	v_lshlrev_b32_e32 v140, 16, v144
	v_and_b32_e32 v141, 0xffff0000, v144
	v_and_b32_e32 v143, 0xffff0000, v145
	v_pk_fma_f32 v[134:135], v[80:81], v[4:5], v[134:135] op_sel_hi:[0,1,1]
	v_fmac_f32_e32 v160, v147, v147
	v_pk_fma_f32 v[144:145], v[80:81], v[6:7], v[138:139] op_sel_hi:[0,1,1]
	v_pk_fma_f32 v[142:143], v[80:81], v[2:3], v[142:143] op_sel_hi:[0,1,1]
	v_pk_fma_f32 v[146:147], v[80:81], v[0:1], v[140:141] op_sel_hi:[0,1,1]
	v_mul_f32_e32 v80, v135, v135
	v_fmac_f32_e32 v80, v134, v134
	v_fmac_f32_e32 v80, v144, v144
	v_fmac_f32_e32 v80, v145, v145
	v_fmac_f32_e32 v80, v146, v146
	v_fmac_f32_e32 v80, v147, v147
	v_fmac_f32_e32 v160, v150, v150
	v_fmac_f32_e32 v80, v142, v142
	v_fmac_f32_e32 v160, v151, v151
	v_fmac_f32_e32 v80, v143, v143
	v_add_f32_e32 v80, v160, v80
	v_cvt_pk_bf16_f32 v138, v134, v135
	v_cvt_pk_bf16_f32 v139, v144, v145
	v_cvt_pk_bf16_f32 v140, v146, v147
	v_cvt_pk_bf16_f32 v141, v142, v143
	global_store_dwordx4 v[82:83], v[138:141], off offset:256
	v_mov_b32_e32 v82, v80
	s_nop 1
	v_permlane32_swap_b32 v82, v80
	s_nop 1
	s_waitcnt lgkmcnt(0)
	v_add_f32_e32 v80, v80, v82
	v_mov_b32_e32 v82, v80
	s_nop 1
	v_permlane16_swap_b32 v82, v80
	s_nop 1
	s_and_saveexec_b64 s[0:1], s[40:41]
	s_cbranch_execz .LBB0_895
	v_readlane_b32 s10, v253, 47
	v_readlane_b32 s11, v253, 48
	s_waitcnt lgkmcnt(0)
	v_add_f32_e32 v80, v80, v82
	v_lshl_add_u64 v[82:83], v[132:133], 2, s[10:11]
	global_atomic_add_f32 v[82:83], v80, off

.LBB0_953:
	s_cmp_lt_i32 s66, 3
	s_mov_b64 s[0:1], -1
	s_cbranch_scc1 .LBB0_1091
	s_cmp_gt_i32 s66, 3
	s_cbranch_scc0 .LBB0_1088
	s_waitcnt lgkmcnt(0)
	v_mov_b32_e32 v82, v192
	s_movk_i32 s0, 0xffc0
	v_and_b32_e32 v80, 15, v82
	v_ashrrev_i32_e32 v83, 2, v82
	v_bfe_u32 v144, v82, 6, 2
	v_and_or_b32 v145, v83, s0, v80
	v_cmp_lt_u32_e64 s[40:41], 1, v144
	v_lshlrev_b32_e32 v80, 4, v145
	s_and_saveexec_b64 s[0:1], s[40:41]
	s_xor_b64 s[0:1], exec, s[0:1]
	v_lshlrev_b32_e32 v80, 4, v145
	s_or_saveexec_b64 s[0:1], s[0:1]
	v_bfe_u32 v134, v82, 4, 2
	s_xor_b64 exec, exec, s[0:1]
	s_cbranch_execz .LBB0_991
	v_xor_b32_e32 v82, 16, v195
	v_cmp_lt_i32_e32 vcc, v82, v197
	s_add_i32 s7, s30, 0x28000
	v_lshl_add_u32 v137, v144, 2, 16
	v_cndmask_b32_e32 v82, v195, v82, vcc
	v_cmp_lt_i32_e32 vcc, v196, v197
	v_lshlrev_b32_e32 v135, 2, v82
	s_nop 0
	v_cndmask_b32_e32 v82, v195, v196, vcc
	v_lshlrev_b32_e32 v136, 2, v82
	v_add_u32_e32 v82, s7, v145
	v_ashrrev_i32_e32 v83, 31, v82
	v_lshl_add_u64 v[82:83], v[82:83], 2, s[90:91]
	global_load_dword v204, v[82:83], off
	global_load_dword v205, v[82:83], off offset:64
	global_load_dword v206, v[82:83], off offset:128
	global_load_dword v207, v[82:83], off offset:192
	global_load_dword v208, v[82:83], off offset:512
	global_load_dword v209, v[82:83], off offset:576
	global_load_dword v210, v[82:83], off offset:640
	global_load_dword v211, v[82:83], off offset:704
	v_cmp_eq_u32_e32 vcc, 0, v134
	s_waitcnt vmcnt(7)
	v_fmamk_f32 v132, v204, 0x3b800000, v194
	v_cmp_gt_f32_e64 s[42:43], s19, v132
	v_mul_f32_e32 v133, 0x4b800000, v132
	s_nop 0
	v_cndmask_b32_e64 v132, v132, v133, s[42:43]
	v_rsq_f32_e32 v132, v132
	s_nop 0
	v_mul_f32_e32 v133, 0x45800000, v132
	v_cndmask_b32_e64 v132, v132, v133, s[42:43]
	v_pk_mul_f32 v[140:141], v[128:129], v[132:133] op_sel_hi:[1,0]
	v_pk_mul_f32 v[138:139], v[130:131], v[132:133] op_sel_hi:[1,0]
	v_mul_f32_e32 v133, v141, v141
	v_fmac_f32_e32 v133, v140, v140
	v_fmac_f32_e32 v133, v138, v138
	v_fmac_f32_e32 v133, v139, v139
	v_pk_mul_f32 v[140:141], v[124:125], v[132:133] op_sel_hi:[1,0]
	v_pk_mul_f32 v[138:139], v[126:127], v[132:133] op_sel_hi:[1,0]
	v_mul_f32_e32 v141, v141, v141
	v_fmac_f32_e32 v141, v140, v140
	v_fmac_f32_e32 v141, v138, v138
	v_fmac_f32_e32 v141, v139, v139
	v_add_f32_e32 v133, v133, v141
	v_mov_b32_e32 v138, v133
	s_nop 1
	v_permlane32_swap_b32 v138, v133
	s_nop 1
	s_waitcnt lgkmcnt(0)
	v_add_f32_e32 v133, v133, v138
	v_mov_b32_e32 v139, v133
	s_nop 1
	v_permlane16_swap_b32 v139, v133
	s_nop 1
	v_add_u32_e32 v138, v137, v80
	s_and_saveexec_b64 s[10:11], vcc
	s_cbranch_execz .LBB0_960
	s_waitcnt lgkmcnt(0)
	v_add_f32_e32 v133, v133, v139
	ds_write_b32 v138, v133 offset:32768
.LBB0_960:
	s_or_b64 exec, exec, s[10:11]
	v_mov_b32_e32 v133, v132
	v_mov_b32_e32 v140, v132
	v_mov_b32_e32 v141, v132
	v_pk_mul_f32 v[146:147], v[132:133], v[120:121]
	v_pk_mul_f32 v[132:133], v[132:133], v[116:117]
	s_waitcnt lgkmcnt(0)
	v_mul_f32_e32 v139, v147, v147
	v_mul_f32_e32 v133, v133, v133
	v_pk_mul_f32 v[142:143], v[140:141], v[122:123]
	v_fmac_f32_e32 v139, v146, v146
	v_pk_mul_f32 v[140:141], v[140:141], v[118:119]
	v_fmac_f32_e32 v133, v132, v132
	v_fmac_f32_e32 v139, v142, v142
	v_fmac_f32_e32 v133, v140, v140
	v_fmac_f32_e32 v139, v143, v143
	v_fmac_f32_e32 v133, v141, v141
	v_add_f32_e32 v132, v139, v133
	v_mov_b32_e32 v133, v132
	s_nop 1
	v_permlane32_swap_b32 v133, v132
	s_nop 1
	s_waitcnt lgkmcnt(0)
	v_add_f32_e32 v132, v132, v133
	v_mov_b32_e32 v133, v132
	s_nop 1
	v_permlane16_swap_b32 v133, v132
	s_nop 1
	s_and_saveexec_b64 s[10:11], vcc
	s_cbranch_execz .LBB0_962
	s_waitcnt lgkmcnt(0)
	v_add_f32_e32 v132, v132, v133
	ds_write_b32 v138, v132 offset:32776
.LBB0_962:
	s_or_b64 exec, exec, s[10:11]
	s_nop 0
	s_waitcnt vmcnt(6)
	v_fmamk_f32 v132, v205, 0x3b800000, v194
	v_cmp_gt_f32_e64 s[42:43], s19, v132
	s_waitcnt lgkmcnt(0)
	v_mul_f32_e32 v133, 0x4b800000, v132
	v_cndmask_b32_e64 v132, v132, v133, s[42:43]
	v_rsq_f32_e32 v132, v132
	s_nop 0
	v_mul_f32_e32 v133, 0x45800000, v132
	v_cndmask_b32_e64 v132, v132, v133, s[42:43]
	v_mov_b32_e32 v133, 0x100
	v_pk_mul_f32 v[140:141], v[112:113], v[132:133] op_sel_hi:[1,0]
	v_lshl_or_b32 v142, v145, 4, v133
	v_pk_mul_f32 v[138:139], v[114:115], v[132:133] op_sel_hi:[1,0]
	v_mul_f32_e32 v133, v141, v141
	v_fmac_f32_e32 v133, v140, v140
	v_fmac_f32_e32 v133, v138, v138
	v_fmac_f32_e32 v133, v139, v139
	v_pk_mul_f32 v[140:141], v[108:109], v[132:133] op_sel_hi:[1,0]
	v_pk_mul_f32 v[138:139], v[110:111], v[132:133] op_sel_hi:[1,0]
	v_mul_f32_e32 v141, v141, v141
	v_fmac_f32_e32 v141, v140, v140
	v_fmac_f32_e32 v141, v138, v138
	v_fmac_f32_e32 v141, v139, v139
	v_add_f32_e32 v133, v133, v141
	v_mov_b32_e32 v138, v133
	s_nop 1
	v_permlane32_swap_b32 v138, v133
	s_nop 1
	s_waitcnt lgkmcnt(0)
	v_add_f32_e32 v133, v133, v138
	v_mov_b32_e32 v139, v133
	s_nop 1
	v_permlane16_swap_b32 v139, v133
	s_nop 1
	v_add_u32_e32 v138, v137, v142
	s_and_saveexec_b64 s[10:11], vcc
	s_cbranch_execz .LBB0_964
	s_waitcnt lgkmcnt(0)
	v_add_f32_e32 v133, v133, v139
	ds_write_b32 v138, v133 offset:32768
.LBB0_964:
	s_or_b64 exec, exec, s[10:11]
	v_mov_b32_e32 v133, v132
	v_mov_b32_e32 v140, v132
	v_mov_b32_e32 v141, v132
	v_pk_mul_f32 v[146:147], v[132:133], v[104:105]
	v_pk_mul_f32 v[132:133], v[132:133], v[100:101]
	s_waitcnt lgkmcnt(0)
	v_mul_f32_e32 v139, v147, v147
	v_mul_f32_e32 v133, v133, v133
	v_pk_mul_f32 v[142:143], v[140:141], v[106:107]
	v_fmac_f32_e32 v139, v146, v146
	v_pk_mul_f32 v[140:141], v[140:141], v[102:103]
	v_fmac_f32_e32 v133, v132, v132
	v_fmac_f32_e32 v139, v142, v142
	v_fmac_f32_e32 v133, v140, v140
	v_fmac_f32_e32 v139, v143, v143
	v_fmac_f32_e32 v133, v141, v141
	v_add_f32_e32 v132, v139, v133
	v_mov_b32_e32 v133, v132
	s_nop 1
	v_permlane32_swap_b32 v133, v132
	s_nop 1
	s_waitcnt lgkmcnt(0)
	v_add_f32_e32 v132, v132, v133
	v_mov_b32_e32 v133, v132
	s_nop 1
	v_permlane16_swap_b32 v133, v132
	s_nop 1
	s_and_saveexec_b64 s[10:11], vcc
	s_cbranch_execz .LBB0_966
	s_waitcnt lgkmcnt(0)
	v_add_f32_e32 v132, v132, v133
	ds_write_b32 v138, v132 offset:32776
.LBB0_966:
	s_or_b64 exec, exec, s[10:11]
	s_nop 0
	s_waitcnt vmcnt(5)
	v_fmamk_f32 v132, v206, 0x3b800000, v194
	v_cmp_gt_f32_e64 s[42:43], s19, v132
	s_waitcnt lgkmcnt(0)
	v_mul_f32_e32 v133, 0x4b800000, v132
	v_cndmask_b32_e64 v132, v132, v133, s[42:43]
	v_rsq_f32_e32 v132, v132
	s_nop 0
	v_mul_f32_e32 v133, 0x45800000, v132
	v_cndmask_b32_e64 v132, v132, v133, s[42:43]
	v_mov_b32_e32 v133, 0x200
	v_pk_mul_f32 v[140:141], v[96:97], v[132:133] op_sel_hi:[1,0]
	v_lshl_or_b32 v142, v145, 4, v133
	v_pk_mul_f32 v[138:139], v[98:99], v[132:133] op_sel_hi:[1,0]
	v_mul_f32_e32 v133, v141, v141
	v_fmac_f32_e32 v133, v140, v140
	v_fmac_f32_e32 v133, v138, v138
	v_fmac_f32_e32 v133, v139, v139
	v_pk_mul_f32 v[140:141], v[92:93], v[132:133] op_sel_hi:[1,0]
	v_pk_mul_f32 v[138:139], v[94:95], v[132:133] op_sel_hi:[1,0]
	v_mul_f32_e32 v141, v141, v141
	v_fmac_f32_e32 v141, v140, v140
	v_fmac_f32_e32 v141, v138, v138
	v_fmac_f32_e32 v141, v139, v139
	v_add_f32_e32 v133, v133, v141
	v_mov_b32_e32 v138, v133
	s_nop 1
	v_permlane32_swap_b32 v138, v133
	s_nop 1
	s_waitcnt lgkmcnt(0)
	v_add_f32_e32 v133, v133, v138
	v_mov_b32_e32 v139, v133
	s_nop 1
	v_permlane16_swap_b32 v139, v133
	s_nop 1
	v_add_u32_e32 v138, v137, v142
	s_and_saveexec_b64 s[10:11], vcc
	s_cbranch_execz .LBB0_968
	s_waitcnt lgkmcnt(0)
	v_add_f32_e32 v133, v133, v139
	ds_write_b32 v138, v133 offset:32768
.LBB0_968:
	s_or_b64 exec, exec, s[10:11]
	v_mov_b32_e32 v133, v132
	v_mov_b32_e32 v140, v132
	v_mov_b32_e32 v141, v132
	v_pk_mul_f32 v[146:147], v[132:133], v[88:89]
	v_pk_mul_f32 v[132:133], v[132:133], v[84:85]
	s_waitcnt lgkmcnt(0)
	v_mul_f32_e32 v139, v147, v147
	v_mul_f32_e32 v133, v133, v133
	v_pk_mul_f32 v[142:143], v[140:141], v[90:91]
	v_fmac_f32_e32 v139, v146, v146
	v_pk_mul_f32 v[140:141], v[140:141], v[86:87]
	v_fmac_f32_e32 v133, v132, v132
	v_fmac_f32_e32 v139, v142, v142
	v_fmac_f32_e32 v133, v140, v140
	v_fmac_f32_e32 v139, v143, v143
	v_fmac_f32_e32 v133, v141, v141
	v_add_f32_e32 v132, v139, v133
	v_mov_b32_e32 v133, v132
	s_nop 1
	v_permlane32_swap_b32 v133, v132
	s_nop 1
	s_waitcnt lgkmcnt(0)
	v_add_f32_e32 v132, v132, v133
	v_mov_b32_e32 v133, v132
	s_nop 1
	v_permlane16_swap_b32 v133, v132
	s_nop 1
	s_and_saveexec_b64 s[10:11], vcc
	s_cbranch_execz .LBB0_970
	s_waitcnt lgkmcnt(0)
	v_add_f32_e32 v132, v132, v133
	ds_write_b32 v138, v132 offset:32776
.LBB0_970:
	s_or_b64 exec, exec, s[10:11]
	s_nop 0
	s_waitcnt vmcnt(4)
	v_fmamk_f32 v132, v207, 0x3b800000, v194
	v_cmp_gt_f32_e64 s[42:43], s19, v132
	s_waitcnt lgkmcnt(0)
	v_mul_f32_e32 v133, 0x4b800000, v132
	v_cndmask_b32_e64 v132, v132, v133, s[42:43]
	v_rsq_f32_e32 v132, v132
	s_nop 0
	v_mul_f32_e32 v133, 0x45800000, v132
	v_cndmask_b32_e64 v132, v132, v133, s[42:43]
	v_mov_b32_e32 v133, 0x300
	v_pk_mul_f32 v[140:141], v[76:77], v[132:133] op_sel_hi:[1,0]
	v_lshl_or_b32 v142, v145, 4, v133
	v_pk_mul_f32 v[138:139], v[78:79], v[132:133] op_sel_hi:[1,0]
	v_mul_f32_e32 v133, v141, v141
	v_fmac_f32_e32 v133, v140, v140
	v_fmac_f32_e32 v133, v138, v138
	v_fmac_f32_e32 v133, v139, v139
	v_pk_mul_f32 v[140:141], v[72:73], v[132:133] op_sel_hi:[1,0]
	v_pk_mul_f32 v[138:139], v[74:75], v[132:133] op_sel_hi:[1,0]
	v_mul_f32_e32 v141, v141, v141
	v_fmac_f32_e32 v141, v140, v140
	v_fmac_f32_e32 v141, v138, v138
	v_fmac_f32_e32 v141, v139, v139
	v_add_f32_e32 v133, v133, v141
	v_mov_b32_e32 v138, v133
	s_nop 1
	v_permlane32_swap_b32 v138, v133
	s_nop 1
	s_waitcnt lgkmcnt(0)
	v_add_f32_e32 v133, v133, v138
	v_mov_b32_e32 v139, v133
	s_nop 1
	v_permlane16_swap_b32 v139, v133
	s_nop 1
	v_add_u32_e32 v138, v137, v142
	s_and_saveexec_b64 s[10:11], vcc
	s_cbranch_execz .LBB0_972
	s_waitcnt lgkmcnt(0)
	v_add_f32_e32 v133, v133, v139
	ds_write_b32 v138, v133 offset:32768
.LBB0_972:
	s_or_b64 exec, exec, s[10:11]
	v_mov_b32_e32 v133, v132
	v_mov_b32_e32 v140, v132
	v_mov_b32_e32 v141, v132
	v_pk_mul_f32 v[146:147], v[132:133], v[68:69]
	v_pk_mul_f32 v[132:133], v[132:133], v[64:65]
	s_waitcnt lgkmcnt(0)
	v_mul_f32_e32 v139, v147, v147
	v_mul_f32_e32 v133, v133, v133
	v_pk_mul_f32 v[142:143], v[140:141], v[70:71]
	v_fmac_f32_e32 v139, v146, v146
	v_pk_mul_f32 v[140:141], v[140:141], v[66:67]
	v_fmac_f32_e32 v133, v132, v132
	v_fmac_f32_e32 v139, v142, v142
	v_fmac_f32_e32 v133, v140, v140
	v_fmac_f32_e32 v139, v143, v143
	v_fmac_f32_e32 v133, v141, v141
	v_add_f32_e32 v132, v139, v133
	v_mov_b32_e32 v133, v132
	s_nop 1
	v_permlane32_swap_b32 v133, v132
	s_nop 1
	s_waitcnt lgkmcnt(0)
	v_add_f32_e32 v132, v132, v133
	v_mov_b32_e32 v133, v132
	s_nop 1
	v_permlane16_swap_b32 v133, v132
	s_nop 1
	s_and_saveexec_b64 s[10:11], vcc
	s_cbranch_execz .LBB0_974
	s_waitcnt lgkmcnt(0)
	v_add_f32_e32 v132, v132, v133
	ds_write_b32 v138, v132 offset:32776
.LBB0_974:
	s_or_b64 exec, exec, s[10:11]
	s_nop 0
	v_lshl_add_u32 v142, v145, 4, v199
	s_waitcnt vmcnt(3)
	v_fmamk_f32 v132, v208, 0x3b800000, v194
	v_cmp_gt_f32_e64 s[42:43], s19, v132
	s_waitcnt lgkmcnt(0)
	v_mul_f32_e32 v133, 0x4b800000, v132
	v_cndmask_b32_e64 v132, v132, v133, s[42:43]
	v_rsq_f32_e32 v132, v132
	s_nop 0
	v_mul_f32_e32 v133, 0x45800000, v132
	v_cndmask_b32_e64 v132, v132, v133, s[42:43]
	v_pk_mul_f32 v[140:141], v[60:61], v[132:133] op_sel_hi:[1,0]
	v_pk_mul_f32 v[138:139], v[62:63], v[132:133] op_sel_hi:[1,0]
	v_mul_f32_e32 v133, v141, v141
	v_fmac_f32_e32 v133, v140, v140
	v_fmac_f32_e32 v133, v138, v138
	v_fmac_f32_e32 v133, v139, v139
	v_pk_mul_f32 v[140:141], v[56:57], v[132:133] op_sel_hi:[1,0]
	v_pk_mul_f32 v[138:139], v[58:59], v[132:133] op_sel_hi:[1,0]
	v_mul_f32_e32 v141, v141, v141
	v_fmac_f32_e32 v141, v140, v140
	v_fmac_f32_e32 v141, v138, v138
	v_fmac_f32_e32 v141, v139, v139
	v_add_f32_e32 v133, v133, v141
	v_mov_b32_e32 v138, v133
	s_nop 1
	v_permlane32_swap_b32 v138, v133
	s_nop 1
	s_waitcnt lgkmcnt(0)
	v_add_f32_e32 v133, v133, v138
	v_mov_b32_e32 v139, v133
	s_nop 1
	v_permlane16_swap_b32 v139, v133
	s_nop 1
	v_add_u32_e32 v138, v137, v142
	s_and_saveexec_b64 s[10:11], vcc
	s_cbranch_execz .LBB0_976
	s_waitcnt lgkmcnt(0)
	v_add_f32_e32 v133, v133, v139
	ds_write_b32 v138, v133 offset:32768
.LBB0_976:
	s_or_b64 exec, exec, s[10:11]
	v_mov_b32_e32 v133, v132
	v_mov_b32_e32 v140, v132
	v_mov_b32_e32 v141, v132
	v_pk_mul_f32 v[146:147], v[132:133], v[52:53]
	v_pk_mul_f32 v[132:133], v[132:133], v[48:49]
	s_waitcnt lgkmcnt(0)
	v_mul_f32_e32 v139, v147, v147
	v_mul_f32_e32 v133, v133, v133
	v_pk_mul_f32 v[142:143], v[140:141], v[54:55]
	v_fmac_f32_e32 v139, v146, v146
	v_pk_mul_f32 v[140:141], v[140:141], v[50:51]
	v_fmac_f32_e32 v133, v132, v132
	v_fmac_f32_e32 v139, v142, v142
	v_fmac_f32_e32 v133, v140, v140
	v_fmac_f32_e32 v139, v143, v143
	v_fmac_f32_e32 v133, v141, v141
	v_add_f32_e32 v132, v139, v133
	v_mov_b32_e32 v133, v132
	s_nop 1
	v_permlane32_swap_b32 v133, v132
	s_nop 1
	s_waitcnt lgkmcnt(0)
	v_add_f32_e32 v132, v132, v133
	v_mov_b32_e32 v133, v132
	s_nop 1
	v_permlane16_swap_b32 v133, v132
	s_nop 1
	s_and_saveexec_b64 s[10:11], vcc
	s_cbranch_execz .LBB0_978
	s_waitcnt lgkmcnt(0)
	v_add_f32_e32 v132, v132, v133
	ds_write_b32 v138, v132 offset:32776
.LBB0_978:
	s_or_b64 exec, exec, s[10:11]
	s_nop 0
	s_waitcnt vmcnt(2)
	v_fmamk_f32 v132, v209, 0x3b800000, v194
	v_cmp_gt_f32_e64 s[42:43], s19, v132
	s_waitcnt lgkmcnt(0)
	v_mul_f32_e32 v133, 0x4b800000, v132
	v_cndmask_b32_e64 v132, v132, v133, s[42:43]
	v_rsq_f32_e32 v132, v132
	s_nop 0
	v_mul_f32_e32 v133, 0x45800000, v132
	v_cndmask_b32_e64 v132, v132, v133, s[42:43]
	v_mov_b32_e32 v133, 0x900
	v_pk_mul_f32 v[140:141], v[44:45], v[132:133] op_sel_hi:[1,0]
	v_lshl_add_u32 v142, v145, 4, v133
	v_pk_mul_f32 v[138:139], v[46:47], v[132:133] op_sel_hi:[1,0]
	v_mul_f32_e32 v133, v141, v141
	v_fmac_f32_e32 v133, v140, v140
	v_fmac_f32_e32 v133, v138, v138
	v_fmac_f32_e32 v133, v139, v139
	v_pk_mul_f32 v[140:141], v[40:41], v[132:133] op_sel_hi:[1,0]
	v_pk_mul_f32 v[138:139], v[42:43], v[132:133] op_sel_hi:[1,0]
	v_mul_f32_e32 v141, v141, v141
	v_fmac_f32_e32 v141, v140, v140
	v_fmac_f32_e32 v141, v138, v138
	v_fmac_f32_e32 v141, v139, v139
	v_add_f32_e32 v133, v133, v141
	v_mov_b32_e32 v138, v133
	s_nop 1
	v_permlane32_swap_b32 v138, v133
	s_nop 1
	s_waitcnt lgkmcnt(0)
	v_add_f32_e32 v133, v133, v138
	v_mov_b32_e32 v139, v133
	s_nop 1
	v_permlane16_swap_b32 v139, v133
	s_nop 1
	v_add_u32_e32 v138, v137, v142
	s_and_saveexec_b64 s[10:11], vcc
	s_cbranch_execz .LBB0_980
	s_waitcnt lgkmcnt(0)
	v_add_f32_e32 v133, v133, v139
	ds_write_b32 v138, v133 offset:32768
.LBB0_980:
	s_or_b64 exec, exec, s[10:11]
	v_mov_b32_e32 v133, v132
	v_mov_b32_e32 v140, v132
	v_mov_b32_e32 v141, v132
	v_pk_mul_f32 v[146:147], v[132:133], v[36:37]
	v_pk_mul_f32 v[132:133], v[132:133], v[32:33]
	s_waitcnt lgkmcnt(0)
	v_mul_f32_e32 v139, v147, v147
	v_mul_f32_e32 v133, v133, v133
	v_pk_mul_f32 v[142:143], v[140:141], v[38:39]
	v_fmac_f32_e32 v139, v146, v146
	v_pk_mul_f32 v[140:141], v[140:141], v[34:35]
	v_fmac_f32_e32 v133, v132, v132
	v_fmac_f32_e32 v139, v142, v142
	v_fmac_f32_e32 v133, v140, v140
	v_fmac_f32_e32 v139, v143, v143
	v_fmac_f32_e32 v133, v141, v141
	v_add_f32_e32 v132, v139, v133
	v_mov_b32_e32 v133, v132
	s_nop 1
	v_permlane32_swap_b32 v133, v132
	s_nop 1
	s_waitcnt lgkmcnt(0)
	v_add_f32_e32 v132, v132, v133
	v_mov_b32_e32 v133, v132
	s_nop 1
	v_permlane16_swap_b32 v133, v132
	s_nop 1
	s_and_saveexec_b64 s[10:11], vcc
	s_cbranch_execz .LBB0_982
	s_waitcnt lgkmcnt(0)
	v_add_f32_e32 v132, v132, v133
	ds_write_b32 v138, v132 offset:32776
.LBB0_982:
	s_or_b64 exec, exec, s[10:11]
	s_nop 0
	s_waitcnt vmcnt(1)
	v_fmamk_f32 v132, v210, 0x3b800000, v194
	v_cmp_gt_f32_e64 s[42:43], s19, v132
	s_waitcnt lgkmcnt(0)
	v_mul_f32_e32 v133, 0x4b800000, v132
	v_cndmask_b32_e64 v132, v132, v133, s[42:43]
	v_rsq_f32_e32 v132, v132
	s_nop 0
	v_mul_f32_e32 v133, 0x45800000, v132
	v_cndmask_b32_e64 v132, v132, v133, s[42:43]
	v_mov_b32_e32 v133, 0xa00
	v_pk_mul_f32 v[140:141], v[28:29], v[132:133] op_sel_hi:[1,0]
	v_lshl_add_u32 v142, v145, 4, v133
	v_pk_mul_f32 v[138:139], v[30:31], v[132:133] op_sel_hi:[1,0]
	v_mul_f32_e32 v133, v141, v141
	v_fmac_f32_e32 v133, v140, v140
	v_fmac_f32_e32 v133, v138, v138
	v_fmac_f32_e32 v133, v139, v139
	v_pk_mul_f32 v[140:141], v[24:25], v[132:133] op_sel_hi:[1,0]
	v_pk_mul_f32 v[138:139], v[26:27], v[132:133] op_sel_hi:[1,0]
	v_mul_f32_e32 v141, v141, v141
	v_fmac_f32_e32 v141, v140, v140
	v_fmac_f32_e32 v141, v138, v138
	v_fmac_f32_e32 v141, v139, v139
	v_add_f32_e32 v133, v133, v141
	v_mov_b32_e32 v138, v133
	s_nop 1
	v_permlane32_swap_b32 v138, v133
	s_nop 1
	s_waitcnt lgkmcnt(0)
	v_add_f32_e32 v133, v133, v138
	v_mov_b32_e32 v139, v133
	s_nop 1
	v_permlane16_swap_b32 v139, v133
	s_nop 1
	v_add_u32_e32 v138, v137, v142
	s_and_saveexec_b64 s[10:11], vcc
	s_cbranch_execz .LBB0_984
	s_waitcnt lgkmcnt(0)
	v_add_f32_e32 v133, v133, v139
	ds_write_b32 v138, v133 offset:32768
.LBB0_984:
	s_or_b64 exec, exec, s[10:11]
	v_mov_b32_e32 v133, v132
	v_mov_b32_e32 v140, v132
	v_mov_b32_e32 v141, v132
	v_pk_mul_f32 v[146:147], v[132:133], v[20:21]
	v_pk_mul_f32 v[132:133], v[132:133], v[16:17]
	s_waitcnt lgkmcnt(0)
	v_mul_f32_e32 v139, v147, v147
	v_mul_f32_e32 v133, v133, v133
	v_pk_mul_f32 v[142:143], v[140:141], v[22:23]
	v_fmac_f32_e32 v139, v146, v146
	v_pk_mul_f32 v[140:141], v[140:141], v[18:19]
	v_fmac_f32_e32 v133, v132, v132
	v_fmac_f32_e32 v139, v142, v142
	v_fmac_f32_e32 v133, v140, v140
	v_fmac_f32_e32 v139, v143, v143
	v_fmac_f32_e32 v133, v141, v141
	v_add_f32_e32 v132, v139, v133
	v_mov_b32_e32 v133, v132
	s_nop 1
	v_permlane32_swap_b32 v133, v132
	s_nop 1
	s_waitcnt lgkmcnt(0)
	v_add_f32_e32 v132, v132, v133
	v_mov_b32_e32 v133, v132
	s_nop 1
	v_permlane16_swap_b32 v133, v132
	s_nop 1
	s_and_saveexec_b64 s[10:11], vcc
	s_cbranch_execz .LBB0_986
	s_waitcnt lgkmcnt(0)
	v_add_f32_e32 v132, v132, v133
	ds_write_b32 v138, v132 offset:32776
.LBB0_986:
	s_or_b64 exec, exec, s[10:11]
	s_nop 0
	s_waitcnt vmcnt(0)
	v_fmamk_f32 v82, v211, 0x3b800000, v194
	v_cmp_gt_f32_e64 s[42:43], s19, v82
	v_mul_f32_e32 v83, 0x4b800000, v82
	s_nop 0
	v_cndmask_b32_e64 v82, v82, v83, s[42:43]
	v_rsq_f32_e32 v82, v82
	s_nop 0
	v_mul_f32_e32 v83, 0x45800000, v82
	v_cndmask_b32_e64 v82, v82, v83, s[42:43]
	v_mov_b32_e32 v83, 0xb00
	v_pk_mul_f32 v[138:139], v[12:13], v[82:83] op_sel_hi:[1,0]
	v_lshl_add_u32 v140, v145, 4, v83
	s_waitcnt lgkmcnt(0)
	v_pk_mul_f32 v[132:133], v[14:15], v[82:83] op_sel_hi:[1,0]
	v_mul_f32_e32 v83, v139, v139
	v_fmac_f32_e32 v83, v138, v138
	v_fmac_f32_e32 v83, v132, v132
	v_fmac_f32_e32 v83, v133, v133
	v_pk_mul_f32 v[138:139], v[8:9], v[82:83] op_sel_hi:[1,0]
	v_pk_mul_f32 v[132:133], v[10:11], v[82:83] op_sel_hi:[1,0]
	v_mul_f32_e32 v139, v139, v139
	v_fmac_f32_e32 v139, v138, v138
	v_fmac_f32_e32 v139, v132, v132
	v_fmac_f32_e32 v139, v133, v133
	v_add_f32_e32 v83, v83, v139
	v_mov_b32_e32 v132, v83
	s_nop 1
	v_permlane32_swap_b32 v132, v83
	s_nop 1
	s_waitcnt lgkmcnt(0)
	v_add_f32_e32 v83, v83, v132
	v_mov_b32_e32 v133, v83
	s_nop 1
	v_permlane16_swap_b32 v133, v83
	s_nop 1
	v_add_u32_e32 v132, v137, v140
	s_and_saveexec_b64 s[10:11], vcc
	s_cbranch_execz .LBB0_988
	s_waitcnt lgkmcnt(0)
	v_add_f32_e32 v83, v83, v133
	ds_write_b32 v132, v83 offset:32768
